# PEER gather: half of each XCD's workgroups start the phase 5 us later so that their per-token routing/epilogue gaps do not coincide (smoother L2-fill demand)
# speedup vs baseline: 1.1296x; 1.0062x over previous
.LBB0_1540:
	s_or_b64 exec, exec, s[0:1]
	v_mov_b32_e32 v36, v190
	s_waitcnt lgkmcnt(0)
	s_barrier
	v_readlane_b32 s98, v240, 10
	s_nop 0
	s_bfe_u32 s98, s98, 0x10003
	s_mul_i32 s98, s98, 2
	s_cmp_eq_u32 s98, 0
	s_cbranch_scc1 .Ldsk_a
.Ldsl_a:
	s_sleep 93
	s_add_i32 s98, s98, -1
	s_cmp_lg_u32 s98, 0
	s_cbranch_scc1 .Ldsl_a
.Ldsk_a:
	s_nop 0
	v_and_b32_e32 v166, 63, v36
	v_subrev_co_u32_e64 v0, s[6:7], 16, v166
	v_and_b32_e32 v2, 56, v36
	s_nop 0
	v_cndmask_b32_e64 v1, 0, v166, s[6:7]
	v_cmp_eq_u32_e32 vcc, 16, v2
	v_subrev_u32_e32 v2, 24, v166
	s_or_b64 s[0:1], vcc, s[6:7]
	v_cndmask_b32_e32 v1, v1, v0, vcc
	v_cndmask_b32_e64 v0, 0, 1, vcc
	v_cmp_gt_u32_e32 vcc, 5, v2
	s_and_saveexec_b64 s[4:5], vcc
	v_mov_b32_e32 v0, 2
	s_or_b64 s[0:1], s[0:1], exec
	v_mov_b32_e32 v1, v2
	s_or_b64 exec, exec, s[4:5]
	v_subrev_u32_e32 v2, 29, v166
	v_cmp_gt_u32_e32 vcc, 4, v2
	s_or_b64 s[0:1], vcc, s[0:1]
	s_nop 0
	v_cndmask_b32_e32 v2, v1, v2, vcc
	v_cndmask_b32_e64 v1, v0, 3, vcc
	v_subrev_u32_e32 v0, 33, v166
	v_cmp_gt_u32_e32 vcc, 3, v0
	s_and_saveexec_b64 s[4:5], vcc
	v_mov_b32_e32 v1, 4
	s_or_b64 s[0:1], s[0:1], exec
	v_mov_b32_e32 v2, v0
	s_or_b64 exec, exec, s[4:5]
	v_and_b32_e32 v0, 62, v36
	v_subrev_u32_e32 v3, 36, v166
	v_cmp_eq_u32_e32 vcc, 36, v0
	s_or_b64 s[0:1], vcc, s[0:1]
	s_nop 0
	v_cndmask_b32_e32 v2, v2, v3, vcc
	v_cndmask_b32_e64 v1, v1, 5, vcc
	v_cmp_eq_u32_e32 vcc, 38, v0
	s_and_saveexec_b64 s[4:5], vcc
	v_subrev_u32_e32 v2, 38, v166
	v_mov_b32_e32 v1, 6
	s_or_b64 s[0:1], s[0:1], exec
	s_or_b64 exec, exec, s[4:5]
	v_subrev_u32_e32 v3, 40, v166
	v_cmp_eq_u32_e32 vcc, 40, v0
	s_or_b64 s[0:1], vcc, s[0:1]
	s_nop 0
	v_cndmask_b32_e32 v0, v2, v3, vcc
	v_cndmask_b32_e64 v1, v1, 7, vcc
	v_cmp_eq_u32_e32 vcc, 42, v166
	s_and_saveexec_b64 s[4:5], vcc
	v_mov_b32_e32 v1, 8
	v_mov_b32_e32 v0, 0
	s_or_b64 s[0:1], s[0:1], exec
	s_or_b64 exec, exec, s[4:5]
	v_cmp_eq_u32_e32 vcc, 43, v166
	s_or_b64 s[0:1], vcc, s[0:1]
	s_nop 0
	v_cndmask_b32_e64 v2, v0, 0, vcc
	v_cndmask_b32_e64 v0, v1, 9, vcc
	v_cmp_eq_u32_e32 vcc, 44, v166
	s_and_saveexec_b64 s[4:5], vcc
	v_mov_b32_e32 v0, 10
	v_mov_b32_e32 v2, 0
	s_or_b64 s[0:1], s[0:1], exec
	s_or_b64 exec, exec, s[4:5]
	v_cmp_eq_u32_e32 vcc, 45, v166
	s_or_b64 s[0:1], vcc, s[0:1]
	s_nop 0
	v_cndmask_b32_e64 v2, v2, 0, vcc
	v_cndmask_b32_e64 v1, v0, 11, vcc
	v_cmp_eq_u32_e32 vcc, 46, v166
	s_and_saveexec_b64 s[4:5], vcc
	v_mov_b32_e32 v1, 12
	v_mov_b32_e32 v2, 0
	s_or_b64 s[0:1], s[0:1], exec
	s_or_b64 exec, exec, s[4:5]
	v_cmp_eq_u32_e32 vcc, 47, v166
	s_or_b64 s[0:1], vcc, s[0:1]
	s_nop 0
	v_cndmask_b32_e64 v0, v2, 0, vcc
	v_cndmask_b32_e64 v2, v1, 13, vcc
	v_cmp_eq_u32_e32 vcc, 48, v166
	s_and_saveexec_b64 s[4:5], vcc
	v_mov_b32_e32 v2, 14
	v_mov_b32_e32 v0, 0
	s_or_b64 s[0:1], s[0:1], exec
	s_or_b64 exec, exec, s[4:5]
	v_readlane_b32 s2, v240, 10
	s_cmpk_lt_i32 s2, 0x4000
	s_cselect_b64 s[84:85], -1, 0
	s_cmpk_gt_i32 s2, 0x3fff
	v_readlane_b32 s3, v240, 11
	s_cbranch_scc1 .LBB0_1586
	v_readlane_b32 s2, v240, 10
	v_cmp_eq_u32_e32 vcc, 49, v166
	s_mov_b32 s4, s2
	s_ashr_i32 s5, s2, 31
	s_or_b64 s[0:1], vcc, s[0:1]
	v_ashrrev_i32_e32 v32, 6, v36
	s_lshl_b64 s[4:5], s[4:5], 12
	v_ashrrev_i32_e32 v33, 31, v32
	s_add_u32 s4, s86, s4
	s_addc_u32 s5, s87, s5
	v_lshlrev_b64 v[34:35], 9, v[32:33]
	v_cndmask_b32_e64 v167, v0, 0, vcc
	v_mov_b32_e32 v113, 0
	v_lshl_add_u64 v[0:1], s[4:5], 0, v[34:35]
	v_lshlrev_b32_e32 v112, 1, v166
	v_lshl_add_u64 v[0:1], v[0:1], 0, v[112:113]
	global_load_ushort v3, v[0:1], off
	global_load_ushort v4, v[0:1], off offset:128
	v_cndmask_b32_e64 v171, v2, 15, vcc
	global_load_ushort v2, v[0:1], off offset:256
	s_nop 0
	global_load_ushort v1, v[0:1], off offset:384
	v_mov_b32_e32 v168, 0xffffff00
	v_bfrev_b32_e32 v169, 1
	s_movk_i32 s52, 0xff
	v_or_b32_e32 v170, 64, v166
	v_readlane_b32 s3, v240, 11
	v_writelane_b32 v240, s2, 10
	s_waitcnt vmcnt(3)
	v_lshlrev_b32_e32 v0, 16, v3
	s_waitcnt vmcnt(2)
	v_lshlrev_b32_e32 v3, 16, v4
	v_cmp_lt_i32_e32 vcc, -1, v0
	s_waitcnt vmcnt(1)
	v_lshlrev_b32_e32 v2, 16, v2
	s_waitcnt vmcnt(0)
	v_lshlrev_b32_e32 v1, 16, v1
	v_cndmask_b32_e32 v4, v168, v169, vcc
	v_cmp_lt_i32_e32 vcc, -1, v3
	v_xor_b32_e32 v0, v4, v0
	v_bitop3_b32 v0, v0, s52, v166 bitop3:0x36
	v_cndmask_b32_e32 v5, v168, v169, vcc
	v_xor_b32_e32 v3, v5, v3
	v_bitop3_b32 v3, v3, s52, v170 bitop3:0x36
	v_max_u32_e32 v4, v0, v3
	v_writelane_b32 v240, s3, 11
	s_movk_i32 s3, 0xff00
	v_max_u32_dpp v4, v4, v4 quad_perm:[1,0,3,2] row_mask:0xf bank_mask:0xf bound_ctrl:1
	s_nop 1
	v_max_u32_dpp v4, v4, v4 quad_perm:[2,3,0,1] row_mask:0xf bank_mask:0xf bound_ctrl:1
	s_nop 1
	v_max_u32_dpp v4, v4, v4 row_half_mirror row_mask:0xf bank_mask:0xf bound_ctrl:1
	s_nop 1
	v_max_u32_dpp v4, v4, v4 row_mirror row_mask:0xf bank_mask:0xf bound_ctrl:1
	s_nop 0
	v_readlane_b32 s8, v4, 32
	v_readlane_b32 s9, v4, 48
	v_readlane_b32 s5, v4, 16
	s_max_u32 s8, s8, s9
	v_readlane_b32 s4, v4, 0
	v_mov_b32_e32 v4, s5
	v_mov_b32_e32 v5, s8
	v_max3_u32 v4, s4, v4, v5
	v_cmp_ne_u32_e32 vcc, v0, v4
	v_cmp_eq_u32_e64 s[8:9], 0, v166
	s_nop 0
	v_cndmask_b32_e32 v0, 0, v0, vcc
	v_cmp_ne_u32_e32 vcc, v3, v4
	v_cndmask_b32_e64 v4, 0, v4, s[8:9]
	s_nop 0
	v_cndmask_b32_e32 v3, 0, v3, vcc
	v_max_u32_e32 v5, v0, v3
	s_nop 1
	v_max_u32_dpp v5, v5, v5 quad_perm:[1,0,3,2] row_mask:0xf bank_mask:0xf bound_ctrl:1
	s_nop 1
	v_max_u32_dpp v5, v5, v5 quad_perm:[2,3,0,1] row_mask:0xf bank_mask:0xf bound_ctrl:1
	s_nop 1
	v_max_u32_dpp v5, v5, v5 row_half_mirror row_mask:0xf bank_mask:0xf bound_ctrl:1
	s_nop 1
	v_max_u32_dpp v5, v5, v5 row_mirror row_mask:0xf bank_mask:0xf bound_ctrl:1
	s_nop 0
	v_readlane_b32 s10, v5, 32
	v_readlane_b32 s11, v5, 48
	v_readlane_b32 s5, v5, 16
	s_max_u32 s10, s10, s11
	v_readlane_b32 s4, v5, 0
	v_mov_b32_e32 v5, s5
	v_mov_b32_e32 v6, s10
	v_max3_u32 v5, s4, v5, v6
	v_cmp_ne_u32_e32 vcc, v0, v5
	v_cmp_eq_u32_e64 s[10:11], 1, v166
	s_nop 0
	v_cndmask_b32_e32 v0, 0, v0, vcc
	v_cmp_ne_u32_e32 vcc, v3, v5
	v_cndmask_b32_e64 v4, v4, v5, s[10:11]
	s_nop 0
	v_cndmask_b32_e32 v3, 0, v3, vcc
	v_max_u32_e32 v5, v0, v3
	s_nop 1
	v_max_u32_dpp v5, v5, v5 quad_perm:[1,0,3,2] row_mask:0xf bank_mask:0xf bound_ctrl:1
	s_nop 1
	v_max_u32_dpp v5, v5, v5 quad_perm:[2,3,0,1] row_mask:0xf bank_mask:0xf bound_ctrl:1
	s_nop 1
	v_max_u32_dpp v5, v5, v5 row_half_mirror row_mask:0xf bank_mask:0xf bound_ctrl:1
	s_nop 1
	v_max_u32_dpp v5, v5, v5 row_mirror row_mask:0xf bank_mask:0xf bound_ctrl:1
	s_nop 0
	v_readlane_b32 s12, v5, 32
	v_readlane_b32 s13, v5, 48
	v_readlane_b32 s5, v5, 16
	s_max_u32 s12, s12, s13
	v_readlane_b32 s4, v5, 0
	v_mov_b32_e32 v5, s5
	v_mov_b32_e32 v6, s12
	v_max3_u32 v5, s4, v5, v6
	v_cmp_ne_u32_e32 vcc, v0, v5
	v_cmp_eq_u32_e64 s[12:13], 2, v166
	s_nop 0
	v_cndmask_b32_e32 v0, 0, v0, vcc
	v_cmp_ne_u32_e32 vcc, v3, v5
	v_cndmask_b32_e64 v4, v4, v5, s[12:13]
	s_nop 0
	v_cndmask_b32_e32 v3, 0, v3, vcc
	v_max_u32_e32 v5, v0, v3
	s_nop 1
	v_max_u32_dpp v5, v5, v5 quad_perm:[1,0,3,2] row_mask:0xf bank_mask:0xf bound_ctrl:1
	s_nop 1
	v_max_u32_dpp v5, v5, v5 quad_perm:[2,3,0,1] row_mask:0xf bank_mask:0xf bound_ctrl:1
	s_nop 1
	v_max_u32_dpp v5, v5, v5 row_half_mirror row_mask:0xf bank_mask:0xf bound_ctrl:1
	s_nop 1
	v_max_u32_dpp v5, v5, v5 row_mirror row_mask:0xf bank_mask:0xf bound_ctrl:1
	s_nop 0
	v_readlane_b32 s14, v5, 32
	v_readlane_b32 s15, v5, 48
	v_readlane_b32 s5, v5, 16
	s_max_u32 s14, s14, s15
	v_readlane_b32 s4, v5, 0
	v_mov_b32_e32 v5, s5
	v_mov_b32_e32 v6, s14
	v_max3_u32 v5, s4, v5, v6
	v_cmp_ne_u32_e32 vcc, v0, v5
	v_cmp_eq_u32_e64 s[14:15], 3, v166
	s_nop 0
	v_cndmask_b32_e32 v0, 0, v0, vcc
	v_cmp_ne_u32_e32 vcc, v3, v5
	v_cndmask_b32_e64 v4, v4, v5, s[14:15]
	s_nop 0
	v_cndmask_b32_e32 v3, 0, v3, vcc
	v_max_u32_e32 v5, v0, v3
	s_nop 1
	v_max_u32_dpp v5, v5, v5 quad_perm:[1,0,3,2] row_mask:0xf bank_mask:0xf bound_ctrl:1
	s_nop 1
	v_max_u32_dpp v5, v5, v5 quad_perm:[2,3,0,1] row_mask:0xf bank_mask:0xf bound_ctrl:1
	s_nop 1
	v_max_u32_dpp v5, v5, v5 row_half_mirror row_mask:0xf bank_mask:0xf bound_ctrl:1
	s_nop 1
	v_max_u32_dpp v5, v5, v5 row_mirror row_mask:0xf bank_mask:0xf bound_ctrl:1
	s_nop 0
	v_readlane_b32 s16, v5, 32
	v_readlane_b32 s17, v5, 48
	v_readlane_b32 s5, v5, 16
	s_max_u32 s16, s16, s17
	v_readlane_b32 s4, v5, 0
	v_mov_b32_e32 v5, s5
	v_mov_b32_e32 v6, s16
	v_max3_u32 v5, s4, v5, v6
	v_cmp_ne_u32_e32 vcc, v0, v5
	v_cmp_eq_u32_e64 s[16:17], 4, v166
	s_nop 0
	v_cndmask_b32_e32 v0, 0, v0, vcc
	v_cmp_ne_u32_e32 vcc, v3, v5
	v_cndmask_b32_e64 v4, v4, v5, s[16:17]
	s_nop 0
	v_cndmask_b32_e32 v3, 0, v3, vcc
	v_max_u32_e32 v5, v0, v3
	s_nop 1
	v_max_u32_dpp v5, v5, v5 quad_perm:[1,0,3,2] row_mask:0xf bank_mask:0xf bound_ctrl:1
	s_nop 1
	v_max_u32_dpp v5, v5, v5 quad_perm:[2,3,0,1] row_mask:0xf bank_mask:0xf bound_ctrl:1
	s_nop 1
	v_max_u32_dpp v5, v5, v5 row_half_mirror row_mask:0xf bank_mask:0xf bound_ctrl:1
	s_nop 1
	v_max_u32_dpp v5, v5, v5 row_mirror row_mask:0xf bank_mask:0xf bound_ctrl:1
	s_nop 0
	v_readlane_b32 s18, v5, 32
	v_readlane_b32 s19, v5, 48
	v_readlane_b32 s5, v5, 16
	s_max_u32 s18, s18, s19
	v_readlane_b32 s4, v5, 0
	v_mov_b32_e32 v5, s5
	v_mov_b32_e32 v6, s18
	v_max3_u32 v5, s4, v5, v6
	v_cmp_ne_u32_e32 vcc, v0, v5
	v_cmp_eq_u32_e64 s[18:19], 5, v166
	s_nop 0
	v_cndmask_b32_e32 v0, 0, v0, vcc
	v_cmp_ne_u32_e32 vcc, v3, v5
	v_cndmask_b32_e64 v4, v4, v5, s[18:19]
	s_nop 0
	v_cndmask_b32_e32 v3, 0, v3, vcc
	v_max_u32_e32 v5, v0, v3
	s_nop 1
	v_max_u32_dpp v5, v5, v5 quad_perm:[1,0,3,2] row_mask:0xf bank_mask:0xf bound_ctrl:1
	s_nop 1
	v_max_u32_dpp v5, v5, v5 quad_perm:[2,3,0,1] row_mask:0xf bank_mask:0xf bound_ctrl:1
	s_nop 1
	v_max_u32_dpp v5, v5, v5 row_half_mirror row_mask:0xf bank_mask:0xf bound_ctrl:1
	s_nop 1
	v_max_u32_dpp v5, v5, v5 row_mirror row_mask:0xf bank_mask:0xf bound_ctrl:1
	s_nop 0
	v_readlane_b32 s20, v5, 32
	v_readlane_b32 s21, v5, 48
	v_readlane_b32 s5, v5, 16
	s_max_u32 s20, s20, s21
	v_readlane_b32 s4, v5, 0
	v_mov_b32_e32 v5, s5
	v_mov_b32_e32 v6, s20
	v_max3_u32 v5, s4, v5, v6
	v_cmp_ne_u32_e32 vcc, v0, v5
	v_cmp_eq_u32_e64 s[20:21], 6, v166
	s_nop 0
	v_cndmask_b32_e32 v0, 0, v0, vcc
	v_cmp_ne_u32_e32 vcc, v3, v5
	v_cndmask_b32_e64 v4, v4, v5, s[20:21]
	s_nop 0
	v_cndmask_b32_e32 v3, 0, v3, vcc
	v_max_u32_e32 v5, v0, v3
	s_nop 1
	v_max_u32_dpp v5, v5, v5 quad_perm:[1,0,3,2] row_mask:0xf bank_mask:0xf bound_ctrl:1
	s_nop 1
	v_max_u32_dpp v5, v5, v5 quad_perm:[2,3,0,1] row_mask:0xf bank_mask:0xf bound_ctrl:1
	s_nop 1
	v_max_u32_dpp v5, v5, v5 row_half_mirror row_mask:0xf bank_mask:0xf bound_ctrl:1
	s_nop 1
	v_max_u32_dpp v5, v5, v5 row_mirror row_mask:0xf bank_mask:0xf bound_ctrl:1
	s_nop 0
	v_readlane_b32 s22, v5, 32
	v_readlane_b32 s23, v5, 48
	v_readlane_b32 s5, v5, 16
	s_max_u32 s22, s22, s23
	v_readlane_b32 s4, v5, 0
	v_mov_b32_e32 v5, s5
	v_mov_b32_e32 v6, s22
	v_max3_u32 v5, s4, v5, v6
	v_cmp_ne_u32_e32 vcc, v0, v5
	v_cmp_eq_u32_e64 s[22:23], 7, v166
	s_nop 0
	v_cndmask_b32_e32 v0, 0, v0, vcc
	v_cmp_ne_u32_e32 vcc, v3, v5
	v_cndmask_b32_e64 v4, v4, v5, s[22:23]
	s_nop 0
	v_cndmask_b32_e32 v3, 0, v3, vcc
	v_max_u32_e32 v5, v0, v3
	s_nop 1
	v_max_u32_dpp v5, v5, v5 quad_perm:[1,0,3,2] row_mask:0xf bank_mask:0xf bound_ctrl:1
	s_nop 1
	v_max_u32_dpp v5, v5, v5 quad_perm:[2,3,0,1] row_mask:0xf bank_mask:0xf bound_ctrl:1
	s_nop 1
	v_max_u32_dpp v5, v5, v5 row_half_mirror row_mask:0xf bank_mask:0xf bound_ctrl:1
	s_nop 1
	v_max_u32_dpp v5, v5, v5 row_mirror row_mask:0xf bank_mask:0xf bound_ctrl:1
	s_nop 0
	v_readlane_b32 s24, v5, 32
	v_readlane_b32 s25, v5, 48
	v_readlane_b32 s5, v5, 16
	s_max_u32 s24, s24, s25
	v_readlane_b32 s4, v5, 0
	v_mov_b32_e32 v5, s5
	v_mov_b32_e32 v6, s24
	v_max3_u32 v5, s4, v5, v6
	v_cmp_ne_u32_e32 vcc, v0, v5
	v_cmp_eq_u32_e64 s[24:25], 8, v166
	s_nop 0
	v_cndmask_b32_e32 v0, 0, v0, vcc
	v_cmp_ne_u32_e32 vcc, v3, v5
	v_cndmask_b32_e64 v4, v4, v5, s[24:25]
	s_nop 0
	v_cndmask_b32_e32 v3, 0, v3, vcc
	v_max_u32_e32 v5, v0, v3
	s_nop 1
	v_max_u32_dpp v5, v5, v5 quad_perm:[1,0,3,2] row_mask:0xf bank_mask:0xf bound_ctrl:1
	s_nop 1
	v_max_u32_dpp v5, v5, v5 quad_perm:[2,3,0,1] row_mask:0xf bank_mask:0xf bound_ctrl:1
	s_nop 1
	v_max_u32_dpp v5, v5, v5 row_half_mirror row_mask:0xf bank_mask:0xf bound_ctrl:1
	s_nop 1
	v_max_u32_dpp v5, v5, v5 row_mirror row_mask:0xf bank_mask:0xf bound_ctrl:1
	s_nop 0
	v_readlane_b32 s26, v5, 32
	v_readlane_b32 s27, v5, 48
	v_readlane_b32 s5, v5, 16
	s_max_u32 s26, s26, s27
	v_readlane_b32 s4, v5, 0
	v_mov_b32_e32 v5, s5
	v_mov_b32_e32 v6, s26
	v_max3_u32 v5, s4, v5, v6
	v_cmp_ne_u32_e32 vcc, v0, v5
	v_cmp_eq_u32_e64 s[26:27], 9, v166
	s_nop 0
	v_cndmask_b32_e32 v0, 0, v0, vcc
	v_cmp_ne_u32_e32 vcc, v3, v5
	v_cndmask_b32_e64 v4, v4, v5, s[26:27]
	s_nop 0
	v_cndmask_b32_e32 v3, 0, v3, vcc
	v_max_u32_e32 v5, v0, v3
	s_nop 1
	v_max_u32_dpp v5, v5, v5 quad_perm:[1,0,3,2] row_mask:0xf bank_mask:0xf bound_ctrl:1
	s_nop 1
	v_max_u32_dpp v5, v5, v5 quad_perm:[2,3,0,1] row_mask:0xf bank_mask:0xf bound_ctrl:1
	s_nop 1
	v_max_u32_dpp v5, v5, v5 row_half_mirror row_mask:0xf bank_mask:0xf bound_ctrl:1
	s_nop 1
	v_max_u32_dpp v5, v5, v5 row_mirror row_mask:0xf bank_mask:0xf bound_ctrl:1
	s_nop 0
	v_readlane_b32 s28, v5, 32
	v_readlane_b32 s29, v5, 48
	v_readlane_b32 s5, v5, 16
	s_max_u32 s28, s28, s29
	v_readlane_b32 s4, v5, 0
	v_mov_b32_e32 v5, s5
	v_mov_b32_e32 v6, s28
	v_max3_u32 v5, s4, v5, v6
	v_cmp_ne_u32_e32 vcc, v0, v5
	v_cmp_eq_u32_e64 s[28:29], 10, v166
	s_nop 0
	v_cndmask_b32_e32 v0, 0, v0, vcc
	v_cmp_ne_u32_e32 vcc, v3, v5
	v_cndmask_b32_e64 v4, v4, v5, s[28:29]
	s_nop 0
	v_cndmask_b32_e32 v3, 0, v3, vcc
	v_max_u32_e32 v5, v0, v3
	s_nop 1
	v_max_u32_dpp v5, v5, v5 quad_perm:[1,0,3,2] row_mask:0xf bank_mask:0xf bound_ctrl:1
	s_nop 1
	v_max_u32_dpp v5, v5, v5 quad_perm:[2,3,0,1] row_mask:0xf bank_mask:0xf bound_ctrl:1
	s_nop 1
	v_max_u32_dpp v5, v5, v5 row_half_mirror row_mask:0xf bank_mask:0xf bound_ctrl:1
	s_nop 1
	v_max_u32_dpp v5, v5, v5 row_mirror row_mask:0xf bank_mask:0xf bound_ctrl:1
	s_nop 0
	v_readlane_b32 s30, v5, 32
	v_readlane_b32 s31, v5, 48
	v_readlane_b32 s5, v5, 16
	s_max_u32 s30, s30, s31
	v_readlane_b32 s4, v5, 0
	v_mov_b32_e32 v5, s5
	v_mov_b32_e32 v6, s30
	v_max3_u32 v5, s4, v5, v6
	v_cmp_ne_u32_e32 vcc, v0, v5
	v_cmp_eq_u32_e64 s[30:31], 11, v166
	s_nop 0
	v_cndmask_b32_e32 v0, 0, v0, vcc
	v_cmp_ne_u32_e32 vcc, v3, v5
	v_cndmask_b32_e64 v4, v4, v5, s[30:31]
	s_nop 0
	v_cndmask_b32_e32 v3, 0, v3, vcc
	v_max_u32_e32 v5, v0, v3
	s_nop 1
	v_max_u32_dpp v5, v5, v5 quad_perm:[1,0,3,2] row_mask:0xf bank_mask:0xf bound_ctrl:1
	s_nop 1
	v_max_u32_dpp v5, v5, v5 quad_perm:[2,3,0,1] row_mask:0xf bank_mask:0xf bound_ctrl:1
	s_nop 1
	v_max_u32_dpp v5, v5, v5 row_half_mirror row_mask:0xf bank_mask:0xf bound_ctrl:1
	s_nop 1
	v_max_u32_dpp v5, v5, v5 row_mirror row_mask:0xf bank_mask:0xf bound_ctrl:1
	s_nop 0
	v_readlane_b32 s34, v5, 32
	v_readlane_b32 s35, v5, 48
	v_readlane_b32 s5, v5, 16
	s_max_u32 s34, s34, s35
	v_readlane_b32 s4, v5, 0
	v_mov_b32_e32 v5, s5
	v_mov_b32_e32 v6, s34
	v_max3_u32 v5, s4, v5, v6
	v_cmp_ne_u32_e32 vcc, v0, v5
	v_cmp_eq_u32_e64 s[34:35], 12, v166
	s_nop 0
	v_cndmask_b32_e32 v0, 0, v0, vcc
	v_cmp_ne_u32_e32 vcc, v3, v5
	v_cndmask_b32_e64 v4, v4, v5, s[34:35]
	s_nop 0
	v_cndmask_b32_e32 v3, 0, v3, vcc
	v_max_u32_e32 v5, v0, v3
	s_nop 1
	v_max_u32_dpp v5, v5, v5 quad_perm:[1,0,3,2] row_mask:0xf bank_mask:0xf bound_ctrl:1
	s_nop 1
	v_max_u32_dpp v5, v5, v5 quad_perm:[2,3,0,1] row_mask:0xf bank_mask:0xf bound_ctrl:1
	s_nop 1
	v_max_u32_dpp v5, v5, v5 row_half_mirror row_mask:0xf bank_mask:0xf bound_ctrl:1
	s_nop 1
	v_max_u32_dpp v5, v5, v5 row_mirror row_mask:0xf bank_mask:0xf bound_ctrl:1
	s_nop 0
	v_readlane_b32 s36, v5, 32
	v_readlane_b32 s37, v5, 48
	v_readlane_b32 s5, v5, 16
	s_max_u32 s36, s36, s37
	v_readlane_b32 s4, v5, 0
	v_mov_b32_e32 v5, s5
	v_mov_b32_e32 v6, s36
	v_max3_u32 v5, s4, v5, v6
	v_cmp_ne_u32_e32 vcc, v0, v5
	v_cmp_eq_u32_e64 s[36:37], 13, v166
	s_nop 0
	v_cndmask_b32_e32 v0, 0, v0, vcc
	v_cmp_ne_u32_e32 vcc, v3, v5
	v_cndmask_b32_e64 v4, v4, v5, s[36:37]
	s_nop 0
	v_cndmask_b32_e32 v3, 0, v3, vcc
	v_max_u32_e32 v5, v0, v3
	s_nop 1
	v_max_u32_dpp v5, v5, v5 quad_perm:[1,0,3,2] row_mask:0xf bank_mask:0xf bound_ctrl:1
	s_nop 1
	v_max_u32_dpp v5, v5, v5 quad_perm:[2,3,0,1] row_mask:0xf bank_mask:0xf bound_ctrl:1
	s_nop 1
	v_max_u32_dpp v5, v5, v5 row_half_mirror row_mask:0xf bank_mask:0xf bound_ctrl:1
	s_nop 1
	v_max_u32_dpp v5, v5, v5 row_mirror row_mask:0xf bank_mask:0xf bound_ctrl:1
	s_nop 0
	v_readlane_b32 s38, v5, 32
	v_readlane_b32 s39, v5, 48
	v_readlane_b32 s5, v5, 16
	s_max_u32 s38, s38, s39
	v_readlane_b32 s4, v5, 0
	v_mov_b32_e32 v5, s5
	v_mov_b32_e32 v6, s38
	v_max3_u32 v5, s4, v5, v6
	v_cmp_ne_u32_e32 vcc, v3, v5
	v_cmp_eq_u32_e64 s[38:39], 14, v166
	s_nop 0
	v_cndmask_b32_e32 v3, 0, v3, vcc
	v_max_u32_e32 v6, v0, v3
	v_cmp_eq_u32_e32 vcc, v0, v5
	v_cndmask_b32_e64 v4, v4, v5, s[38:39]
	s_nop 0
	v_cndmask_b32_e32 v0, v6, v3, vcc
	v_cmp_lt_i32_e32 vcc, -1, v2
	s_nop 0
	v_max_u32_dpp v0, v0, v0 quad_perm:[1,0,3,2] row_mask:0xf bank_mask:0xf bound_ctrl:1
	s_nop 1
	v_max_u32_dpp v0, v0, v0 quad_perm:[2,3,0,1] row_mask:0xf bank_mask:0xf bound_ctrl:1
	s_nop 1
	v_max_u32_dpp v0, v0, v0 row_half_mirror row_mask:0xf bank_mask:0xf bound_ctrl:1
	s_nop 1
	v_max_u32_dpp v0, v0, v0 row_mirror row_mask:0xf bank_mask:0xf bound_ctrl:1
	s_nop 0
	v_readlane_b32 s40, v0, 32
	v_readlane_b32 s41, v0, 48
	v_readlane_b32 s5, v0, 16
	s_max_u32 s40, s40, s41
	v_readlane_b32 s4, v0, 0
	v_mov_b32_e32 v0, s5
	v_mov_b32_e32 v3, s40
	v_max3_u32 v0, s4, v0, v3
	v_cndmask_b32_e32 v3, v168, v169, vcc
	v_cmp_lt_i32_e32 vcc, -1, v1
	v_xor_b32_e32 v2, v3, v2
	v_bitop3_b32 v2, v2, s52, v166 bitop3:0x36
	v_cndmask_b32_e32 v3, v168, v169, vcc
	v_xor_b32_e32 v1, v3, v1
	v_bitop3_b32 v1, v1, s52, v170 bitop3:0x36
	v_max_u32_e32 v3, v2, v1
	v_cmp_eq_u32_e64 s[40:41], 15, v166
	s_nop 0
	v_max_u32_dpp v3, v3, v3 quad_perm:[1,0,3,2] row_mask:0xf bank_mask:0xf bound_ctrl:1
	v_cndmask_b32_e64 v0, v4, v0, s[40:41]
	s_nop 0
	v_max_u32_dpp v3, v3, v3 quad_perm:[2,3,0,1] row_mask:0xf bank_mask:0xf bound_ctrl:1
	s_nop 1
	v_max_u32_dpp v3, v3, v3 row_half_mirror row_mask:0xf bank_mask:0xf bound_ctrl:1
	s_nop 1
	v_max_u32_dpp v3, v3, v3 row_mirror row_mask:0xf bank_mask:0xf bound_ctrl:1
	s_nop 0
	v_readlane_b32 s42, v3, 32
	v_readlane_b32 s43, v3, 48
	v_readlane_b32 s5, v3, 16
	s_max_u32 s42, s42, s43
	v_readlane_b32 s4, v3, 0
	v_mov_b32_e32 v3, s5
	v_mov_b32_e32 v4, s42
	v_max3_u32 v3, s4, v3, v4
	v_cmp_ne_u32_e32 vcc, v2, v3
	s_nop 1
	v_cndmask_b32_e32 v2, 0, v2, vcc
	v_cmp_ne_u32_e32 vcc, v1, v3
	v_cndmask_b32_e64 v3, 0, v3, s[8:9]
	s_nop 0
	v_cndmask_b32_e32 v1, 0, v1, vcc
	v_max_u32_e32 v4, v2, v1
	s_nop 1
	v_max_u32_dpp v4, v4, v4 quad_perm:[1,0,3,2] row_mask:0xf bank_mask:0xf bound_ctrl:1
	s_nop 1
	v_max_u32_dpp v4, v4, v4 quad_perm:[2,3,0,1] row_mask:0xf bank_mask:0xf bound_ctrl:1
	s_nop 1
	v_max_u32_dpp v4, v4, v4 row_half_mirror row_mask:0xf bank_mask:0xf bound_ctrl:1
	s_nop 1
	v_max_u32_dpp v4, v4, v4 row_mirror row_mask:0xf bank_mask:0xf bound_ctrl:1
	s_nop 0
	v_readlane_b32 s42, v4, 32
	v_readlane_b32 s43, v4, 48
	v_readlane_b32 s5, v4, 16
	s_max_u32 s42, s42, s43
	v_readlane_b32 s4, v4, 0
	v_mov_b32_e32 v4, s5
	v_mov_b32_e32 v5, s42
	v_max3_u32 v4, s4, v4, v5
	v_cmp_ne_u32_e32 vcc, v2, v4
	v_cndmask_b32_e64 v3, v3, v4, s[10:11]
	s_nop 0
	v_cndmask_b32_e32 v2, 0, v2, vcc
	v_cmp_ne_u32_e32 vcc, v1, v4
	s_nop 1
	v_cndmask_b32_e32 v1, 0, v1, vcc
	v_max_u32_e32 v4, v2, v1
	s_nop 1
	v_max_u32_dpp v4, v4, v4 quad_perm:[1,0,3,2] row_mask:0xf bank_mask:0xf bound_ctrl:1
	s_nop 1
	v_max_u32_dpp v4, v4, v4 quad_perm:[2,3,0,1] row_mask:0xf bank_mask:0xf bound_ctrl:1
	s_nop 1
	v_max_u32_dpp v4, v4, v4 row_half_mirror row_mask:0xf bank_mask:0xf bound_ctrl:1
	s_nop 1
	v_max_u32_dpp v4, v4, v4 row_mirror row_mask:0xf bank_mask:0xf bound_ctrl:1
	s_nop 0
	v_readlane_b32 s42, v4, 32
	v_readlane_b32 s43, v4, 48
	v_readlane_b32 s5, v4, 16
	s_max_u32 s42, s42, s43
	v_readlane_b32 s4, v4, 0
	v_mov_b32_e32 v4, s5
	v_mov_b32_e32 v5, s42
	v_max3_u32 v4, s4, v4, v5
	v_cmp_ne_u32_e32 vcc, v2, v4
	v_cndmask_b32_e64 v3, v3, v4, s[12:13]
	s_nop 0
	v_cndmask_b32_e32 v2, 0, v2, vcc
	v_cmp_ne_u32_e32 vcc, v1, v4
	s_nop 1
	v_cndmask_b32_e32 v1, 0, v1, vcc
	v_max_u32_e32 v4, v2, v1
	s_nop 1
	v_max_u32_dpp v4, v4, v4 quad_perm:[1,0,3,2] row_mask:0xf bank_mask:0xf bound_ctrl:1
	s_nop 1
	v_max_u32_dpp v4, v4, v4 quad_perm:[2,3,0,1] row_mask:0xf bank_mask:0xf bound_ctrl:1
	s_nop 1
	v_max_u32_dpp v4, v4, v4 row_half_mirror row_mask:0xf bank_mask:0xf bound_ctrl:1
	s_nop 1
	v_max_u32_dpp v4, v4, v4 row_mirror row_mask:0xf bank_mask:0xf bound_ctrl:1
	s_nop 0
	v_readlane_b32 s42, v4, 32
	v_readlane_b32 s43, v4, 48
	v_readlane_b32 s5, v4, 16
	s_max_u32 s42, s42, s43
	v_readlane_b32 s4, v4, 0
	v_mov_b32_e32 v4, s5
	v_mov_b32_e32 v5, s42
	v_max3_u32 v4, s4, v4, v5
	v_cmp_ne_u32_e32 vcc, v2, v4
	v_cndmask_b32_e64 v3, v3, v4, s[14:15]
	s_nop 0
	v_cndmask_b32_e32 v2, 0, v2, vcc
	v_cmp_ne_u32_e32 vcc, v1, v4
	s_nop 1
	v_cndmask_b32_e32 v1, 0, v1, vcc
	v_max_u32_e32 v4, v2, v1
	s_nop 1
	v_max_u32_dpp v4, v4, v4 quad_perm:[1,0,3,2] row_mask:0xf bank_mask:0xf bound_ctrl:1
	s_nop 1
	v_max_u32_dpp v4, v4, v4 quad_perm:[2,3,0,1] row_mask:0xf bank_mask:0xf bound_ctrl:1
	s_nop 1
	v_max_u32_dpp v4, v4, v4 row_half_mirror row_mask:0xf bank_mask:0xf bound_ctrl:1
	s_nop 1
	v_max_u32_dpp v4, v4, v4 row_mirror row_mask:0xf bank_mask:0xf bound_ctrl:1
	s_nop 0
	v_readlane_b32 s42, v4, 32
	v_readlane_b32 s43, v4, 48
	v_readlane_b32 s5, v4, 16
	s_max_u32 s42, s42, s43
	v_readlane_b32 s4, v4, 0
	v_mov_b32_e32 v4, s5
	v_mov_b32_e32 v5, s42
	v_max3_u32 v4, s4, v4, v5
	v_cmp_ne_u32_e32 vcc, v2, v4
	v_cndmask_b32_e64 v3, v3, v4, s[16:17]
	s_nop 0
	v_cndmask_b32_e32 v2, 0, v2, vcc
	v_cmp_ne_u32_e32 vcc, v1, v4
	s_nop 1
	v_cndmask_b32_e32 v1, 0, v1, vcc
	v_max_u32_e32 v4, v2, v1
	s_nop 1
	v_max_u32_dpp v4, v4, v4 quad_perm:[1,0,3,2] row_mask:0xf bank_mask:0xf bound_ctrl:1
	s_nop 1
	v_max_u32_dpp v4, v4, v4 quad_perm:[2,3,0,1] row_mask:0xf bank_mask:0xf bound_ctrl:1
	s_nop 1
	v_max_u32_dpp v4, v4, v4 row_half_mirror row_mask:0xf bank_mask:0xf bound_ctrl:1
	s_nop 1
	v_max_u32_dpp v4, v4, v4 row_mirror row_mask:0xf bank_mask:0xf bound_ctrl:1
	s_nop 0
	v_readlane_b32 s42, v4, 32
	v_readlane_b32 s43, v4, 48
	v_readlane_b32 s5, v4, 16
	s_max_u32 s42, s42, s43
	v_readlane_b32 s4, v4, 0
	v_mov_b32_e32 v4, s5
	v_mov_b32_e32 v5, s42
	v_max3_u32 v4, s4, v4, v5
	v_cmp_ne_u32_e32 vcc, v2, v4
	v_cndmask_b32_e64 v3, v3, v4, s[18:19]
	s_nop 0
	v_cndmask_b32_e32 v2, 0, v2, vcc
	v_cmp_ne_u32_e32 vcc, v1, v4
	s_nop 1
	v_cndmask_b32_e32 v1, 0, v1, vcc
	v_max_u32_e32 v4, v2, v1
	s_nop 1
	v_max_u32_dpp v4, v4, v4 quad_perm:[1,0,3,2] row_mask:0xf bank_mask:0xf bound_ctrl:1
	s_nop 1
	v_max_u32_dpp v4, v4, v4 quad_perm:[2,3,0,1] row_mask:0xf bank_mask:0xf bound_ctrl:1
	s_nop 1
	v_max_u32_dpp v4, v4, v4 row_half_mirror row_mask:0xf bank_mask:0xf bound_ctrl:1
	s_nop 1
	v_max_u32_dpp v4, v4, v4 row_mirror row_mask:0xf bank_mask:0xf bound_ctrl:1
	s_nop 0
	v_readlane_b32 s42, v4, 32
	v_readlane_b32 s43, v4, 48
	v_readlane_b32 s5, v4, 16
	s_max_u32 s42, s42, s43
	v_readlane_b32 s4, v4, 0
	v_mov_b32_e32 v4, s5
	v_mov_b32_e32 v5, s42
	v_max3_u32 v4, s4, v4, v5
	v_cmp_ne_u32_e32 vcc, v2, v4
	v_cndmask_b32_e64 v3, v3, v4, s[20:21]
	s_nop 0
	v_cndmask_b32_e32 v2, 0, v2, vcc
	v_cmp_ne_u32_e32 vcc, v1, v4
	s_nop 1
	v_cndmask_b32_e32 v1, 0, v1, vcc
	v_max_u32_e32 v4, v2, v1
	s_nop 1
	v_max_u32_dpp v4, v4, v4 quad_perm:[1,0,3,2] row_mask:0xf bank_mask:0xf bound_ctrl:1
	s_nop 1
	v_max_u32_dpp v4, v4, v4 quad_perm:[2,3,0,1] row_mask:0xf bank_mask:0xf bound_ctrl:1
	s_nop 1
	v_max_u32_dpp v4, v4, v4 row_half_mirror row_mask:0xf bank_mask:0xf bound_ctrl:1
	s_nop 1
	v_max_u32_dpp v4, v4, v4 row_mirror row_mask:0xf bank_mask:0xf bound_ctrl:1
	s_nop 0
	v_readlane_b32 s42, v4, 32
	v_readlane_b32 s43, v4, 48
	v_readlane_b32 s5, v4, 16
	s_max_u32 s42, s42, s43
	v_readlane_b32 s4, v4, 0
	v_mov_b32_e32 v4, s5
	v_mov_b32_e32 v5, s42
	v_max3_u32 v4, s4, v4, v5
	v_cmp_ne_u32_e32 vcc, v2, v4
	v_cndmask_b32_e64 v3, v3, v4, s[22:23]
	s_nop 0
	v_cndmask_b32_e32 v2, 0, v2, vcc
	v_cmp_ne_u32_e32 vcc, v1, v4
	s_nop 1
	v_cndmask_b32_e32 v1, 0, v1, vcc
	v_max_u32_e32 v4, v2, v1
	s_nop 1
	v_max_u32_dpp v4, v4, v4 quad_perm:[1,0,3,2] row_mask:0xf bank_mask:0xf bound_ctrl:1
	s_nop 1
	v_max_u32_dpp v4, v4, v4 quad_perm:[2,3,0,1] row_mask:0xf bank_mask:0xf bound_ctrl:1
	s_nop 1
	v_max_u32_dpp v4, v4, v4 row_half_mirror row_mask:0xf bank_mask:0xf bound_ctrl:1
	s_nop 1
	v_max_u32_dpp v4, v4, v4 row_mirror row_mask:0xf bank_mask:0xf bound_ctrl:1
	s_nop 0
	v_readlane_b32 s42, v4, 32
	v_readlane_b32 s43, v4, 48
	v_readlane_b32 s5, v4, 16
	s_max_u32 s42, s42, s43
	v_readlane_b32 s4, v4, 0
	v_mov_b32_e32 v4, s5
	v_mov_b32_e32 v5, s42
	v_max3_u32 v4, s4, v4, v5
	v_cmp_ne_u32_e32 vcc, v2, v4
	v_cndmask_b32_e64 v3, v3, v4, s[24:25]
	s_nop 0
	v_cndmask_b32_e32 v2, 0, v2, vcc
	v_cmp_ne_u32_e32 vcc, v1, v4
	s_nop 1
	v_cndmask_b32_e32 v1, 0, v1, vcc
	v_max_u32_e32 v4, v2, v1
	s_nop 1
	v_max_u32_dpp v4, v4, v4 quad_perm:[1,0,3,2] row_mask:0xf bank_mask:0xf bound_ctrl:1
	s_nop 1
	v_max_u32_dpp v4, v4, v4 quad_perm:[2,3,0,1] row_mask:0xf bank_mask:0xf bound_ctrl:1
	s_nop 1
	v_max_u32_dpp v4, v4, v4 row_half_mirror row_mask:0xf bank_mask:0xf bound_ctrl:1
	s_nop 1
	v_max_u32_dpp v4, v4, v4 row_mirror row_mask:0xf bank_mask:0xf bound_ctrl:1
	s_nop 0
	v_readlane_b32 s42, v4, 32
	v_readlane_b32 s43, v4, 48
	v_readlane_b32 s5, v4, 16
	s_max_u32 s42, s42, s43
	v_readlane_b32 s4, v4, 0
	v_mov_b32_e32 v4, s5
	v_mov_b32_e32 v5, s42
	v_max3_u32 v4, s4, v4, v5
	v_cmp_ne_u32_e32 vcc, v2, v4
	v_cndmask_b32_e64 v3, v3, v4, s[26:27]
	s_nop 0
	v_cndmask_b32_e32 v2, 0, v2, vcc
	v_cmp_ne_u32_e32 vcc, v1, v4
	s_nop 1
	v_cndmask_b32_e32 v1, 0, v1, vcc
	v_max_u32_e32 v4, v2, v1
	s_nop 1
	v_max_u32_dpp v4, v4, v4 quad_perm:[1,0,3,2] row_mask:0xf bank_mask:0xf bound_ctrl:1
	s_nop 1
	v_max_u32_dpp v4, v4, v4 quad_perm:[2,3,0,1] row_mask:0xf bank_mask:0xf bound_ctrl:1
	s_nop 1
	v_max_u32_dpp v4, v4, v4 row_half_mirror row_mask:0xf bank_mask:0xf bound_ctrl:1
	s_nop 1
	v_max_u32_dpp v4, v4, v4 row_mirror row_mask:0xf bank_mask:0xf bound_ctrl:1
	s_nop 0
	v_readlane_b32 s42, v4, 32
	v_readlane_b32 s43, v4, 48
	v_readlane_b32 s5, v4, 16
	s_max_u32 s42, s42, s43
	v_readlane_b32 s4, v4, 0
	v_mov_b32_e32 v4, s5
	v_mov_b32_e32 v5, s42
	v_max3_u32 v4, s4, v4, v5
	v_cmp_ne_u32_e32 vcc, v2, v4
	v_cndmask_b32_e64 v3, v3, v4, s[28:29]
	s_nop 0
	v_cndmask_b32_e32 v2, 0, v2, vcc
	v_cmp_ne_u32_e32 vcc, v1, v4
	s_nop 1
	v_cndmask_b32_e32 v1, 0, v1, vcc
	v_max_u32_e32 v4, v2, v1
	s_nop 1
	v_max_u32_dpp v4, v4, v4 quad_perm:[1,0,3,2] row_mask:0xf bank_mask:0xf bound_ctrl:1
	s_nop 1
	v_max_u32_dpp v4, v4, v4 quad_perm:[2,3,0,1] row_mask:0xf bank_mask:0xf bound_ctrl:1
	s_nop 1
	v_max_u32_dpp v4, v4, v4 row_half_mirror row_mask:0xf bank_mask:0xf bound_ctrl:1
	s_nop 1
	v_max_u32_dpp v4, v4, v4 row_mirror row_mask:0xf bank_mask:0xf bound_ctrl:1
	s_nop 0
	v_readlane_b32 s42, v4, 32
	v_readlane_b32 s43, v4, 48
	v_readlane_b32 s5, v4, 16
	s_max_u32 s42, s42, s43
	v_readlane_b32 s4, v4, 0
	v_mov_b32_e32 v4, s5
	v_mov_b32_e32 v5, s42
	v_max3_u32 v4, s4, v4, v5
	v_cmp_ne_u32_e32 vcc, v2, v4
	v_cndmask_b32_e64 v3, v3, v4, s[30:31]
	s_nop 0
	v_cndmask_b32_e32 v2, 0, v2, vcc
	v_cmp_ne_u32_e32 vcc, v1, v4
	s_nop 1
	v_cndmask_b32_e32 v1, 0, v1, vcc
	v_max_u32_e32 v4, v2, v1
	s_nop 1
	v_max_u32_dpp v4, v4, v4 quad_perm:[1,0,3,2] row_mask:0xf bank_mask:0xf bound_ctrl:1
	s_nop 1
	v_max_u32_dpp v4, v4, v4 quad_perm:[2,3,0,1] row_mask:0xf bank_mask:0xf bound_ctrl:1
	s_nop 1
	v_max_u32_dpp v4, v4, v4 row_half_mirror row_mask:0xf bank_mask:0xf bound_ctrl:1
	s_nop 1
	v_max_u32_dpp v4, v4, v4 row_mirror row_mask:0xf bank_mask:0xf bound_ctrl:1
	s_nop 0
	v_readlane_b32 s42, v4, 32
	v_readlane_b32 s43, v4, 48
	v_readlane_b32 s5, v4, 16
	s_max_u32 s42, s42, s43
	v_readlane_b32 s4, v4, 0
	v_mov_b32_e32 v4, s5
	v_mov_b32_e32 v5, s42
	v_max3_u32 v4, s4, v4, v5
	v_cmp_ne_u32_e32 vcc, v2, v4
	v_cndmask_b32_e64 v3, v3, v4, s[34:35]
	s_nop 0
	v_cndmask_b32_e32 v2, 0, v2, vcc
	v_cmp_ne_u32_e32 vcc, v1, v4
	s_nop 1
	v_cndmask_b32_e32 v1, 0, v1, vcc
	v_max_u32_e32 v4, v2, v1
	s_nop 1
	v_max_u32_dpp v4, v4, v4 quad_perm:[1,0,3,2] row_mask:0xf bank_mask:0xf bound_ctrl:1
	s_nop 1
	v_max_u32_dpp v4, v4, v4 quad_perm:[2,3,0,1] row_mask:0xf bank_mask:0xf bound_ctrl:1
	s_nop 1
	v_max_u32_dpp v4, v4, v4 row_half_mirror row_mask:0xf bank_mask:0xf bound_ctrl:1
	s_nop 1
	v_max_u32_dpp v4, v4, v4 row_mirror row_mask:0xf bank_mask:0xf bound_ctrl:1
	s_nop 0
	v_readlane_b32 s42, v4, 32
	v_readlane_b32 s43, v4, 48
	v_readlane_b32 s5, v4, 16
	s_max_u32 s42, s42, s43
	v_readlane_b32 s4, v4, 0
	v_mov_b32_e32 v4, s5
	v_mov_b32_e32 v5, s42
	v_max3_u32 v4, s4, v4, v5
	v_cmp_ne_u32_e32 vcc, v2, v4
	v_cndmask_b32_e64 v3, v3, v4, s[36:37]
	s_nop 0
	v_cndmask_b32_e32 v2, 0, v2, vcc
	v_cmp_ne_u32_e32 vcc, v1, v4
	s_nop 1
	v_cndmask_b32_e32 v1, 0, v1, vcc
	v_max_u32_e32 v4, v2, v1
	s_nop 1
	v_max_u32_dpp v4, v4, v4 quad_perm:[1,0,3,2] row_mask:0xf bank_mask:0xf bound_ctrl:1
	s_nop 1
	v_max_u32_dpp v4, v4, v4 quad_perm:[2,3,0,1] row_mask:0xf bank_mask:0xf bound_ctrl:1
	s_nop 1
	v_max_u32_dpp v4, v4, v4 row_half_mirror row_mask:0xf bank_mask:0xf bound_ctrl:1
	s_nop 1
	v_max_u32_dpp v4, v4, v4 row_mirror row_mask:0xf bank_mask:0xf bound_ctrl:1
	s_nop 0
	v_readlane_b32 s42, v4, 32
	v_readlane_b32 s43, v4, 48
	v_readlane_b32 s5, v4, 16
	s_max_u32 s42, s42, s43
	v_readlane_b32 s4, v4, 0
	v_mov_b32_e32 v4, s5
	v_mov_b32_e32 v5, s42
	v_max3_u32 v4, s4, v4, v5
	v_cmp_ne_u32_e32 vcc, v1, v4
	v_cndmask_b32_e64 v3, v3, v4, s[38:39]
	s_nop 0
	v_cndmask_b32_e32 v1, 0, v1, vcc
	v_max_u32_e32 v5, v2, v1
	v_cmp_eq_u32_e32 vcc, v2, v4
	s_nop 1
	v_cndmask_b32_e32 v1, v5, v1, vcc
	v_cmp_lt_i32_e32 vcc, -1, v0
	s_nop 0
	v_max_u32_dpp v1, v1, v1 quad_perm:[1,0,3,2] row_mask:0xf bank_mask:0xf bound_ctrl:1
	s_nop 1
	v_max_u32_dpp v1, v1, v1 quad_perm:[2,3,0,1] row_mask:0xf bank_mask:0xf bound_ctrl:1
	s_nop 1
	v_max_u32_dpp v1, v1, v1 row_half_mirror row_mask:0xf bank_mask:0xf bound_ctrl:1
	s_nop 1
	v_max_u32_dpp v1, v1, v1 row_mirror row_mask:0xf bank_mask:0xf bound_ctrl:1
	s_nop 0
	v_readlane_b32 s42, v1, 32
	v_readlane_b32 s43, v1, 48
	v_readlane_b32 s5, v1, 16
	s_max_u32 s42, s42, s43
	v_readlane_b32 s4, v1, 0
	v_mov_b32_e32 v1, s5
	v_mov_b32_e32 v2, s42
	v_max3_u32 v1, s4, v1, v2
	v_cndmask_b32_e64 v1, v3, v1, s[40:41]
	v_cndmask_b32_e64 v2, v169, -1, vcc
	v_cmp_lt_i32_e32 vcc, -1, v1
	v_bitop3_b32 v2, v2, v0, s3 bitop3:0x78
	s_mov_b32 s5, 0
	v_cndmask_b32_e64 v3, v169, -1, vcc
	v_bitop3_b32 v4, v3, v1, s3 bitop3:0x78
	v_mbcnt_hi_u32_b32 v3, -1, v191
	v_and_b32_e32 v172, 64, v3
	v_or_b32_e32 v3, v172, v171
	v_lshlrev_b32_e32 v173, 2, v3
	v_add_lshl_u32 v174, v172, v167, 2
	ds_bpermute_b32 v3, v173, v2
	ds_bpermute_b32 v4, v174, v4
	v_mov_b32_e32 v2, v113
	s_and_saveexec_b64 s[42:43], s[0:1]
	s_cbranch_execz .LBB0_1557
	s_waitcnt lgkmcnt(0)
	v_add_f32_e32 v2, v3, v4
	v_cmp_lt_i32_e32 vcc, -1, v2
	s_nop 1
	v_cndmask_b32_e32 v3, -1, v169, vcc
	v_bitop3_b32 v2, v3, s3, v2 bitop3:0x48
	v_bitop3_b32 v2, v2, s52, v166 bitop3:0x36

.LBB0_2758:
	s_or_b64 exec, exec, s[0:1]
	s_waitcnt lgkmcnt(0)
	s_barrier
	v_readlane_b32 s98, v240, 10
	s_nop 0
	s_bfe_u32 s98, s98, 0x10003
	s_mul_i32 s98, s98, 2
	s_cmp_eq_u32 s98, 0
	s_cbranch_scc1 .Ldsk_b

.Ldsk_b:
	s_waitcnt vmcnt(1)
	v_and_b32_e32 v156, 63, v190
	v_subrev_co_u32_e64 v0, s[4:5], 16, v156
	v_and_b32_e32 v2, 56, v190
	s_nop 0
	v_cndmask_b32_e64 v1, 0, v156, s[4:5]
	v_cmp_eq_u32_e32 vcc, 16, v2
	v_subrev_u32_e32 v2, 24, v156
	s_or_b64 s[0:1], vcc, s[4:5]
	v_cndmask_b32_e32 v1, v1, v0, vcc
	v_cndmask_b32_e64 v0, 0, 1, vcc
	v_cmp_gt_u32_e32 vcc, 5, v2
	s_and_saveexec_b64 s[6:7], vcc
	v_mov_b32_e32 v0, 2
	s_or_b64 s[0:1], s[0:1], exec
	v_mov_b32_e32 v1, v2
	s_or_b64 exec, exec, s[6:7]
	v_subrev_u32_e32 v2, 29, v156
	v_cmp_gt_u32_e32 vcc, 4, v2
	s_or_b64 s[0:1], vcc, s[0:1]
	s_nop 0
	v_cndmask_b32_e32 v2, v1, v2, vcc
	v_cndmask_b32_e64 v1, v0, 3, vcc
	v_subrev_u32_e32 v0, 33, v156
	v_cmp_gt_u32_e32 vcc, 3, v0
	s_and_saveexec_b64 s[6:7], vcc
	v_mov_b32_e32 v1, 4
	s_or_b64 s[0:1], s[0:1], exec
	v_mov_b32_e32 v2, v0
	s_or_b64 exec, exec, s[6:7]
	v_and_b32_e32 v0, 62, v190
	v_subrev_u32_e32 v3, 36, v156
	v_cmp_eq_u32_e32 vcc, 36, v0
	s_or_b64 s[0:1], vcc, s[0:1]
	s_nop 0
	v_cndmask_b32_e32 v2, v2, v3, vcc
	v_cndmask_b32_e64 v1, v1, 5, vcc
	v_cmp_eq_u32_e32 vcc, 38, v0
	s_and_saveexec_b64 s[6:7], vcc
	v_subrev_u32_e32 v2, 38, v156
	v_mov_b32_e32 v1, 6
	s_or_b64 s[0:1], s[0:1], exec
	s_or_b64 exec, exec, s[6:7]
	v_subrev_u32_e32 v3, 40, v156
	v_cmp_eq_u32_e32 vcc, 40, v0
	s_or_b64 s[0:1], vcc, s[0:1]
	s_nop 0
	v_cndmask_b32_e32 v0, v2, v3, vcc
	v_cndmask_b32_e64 v1, v1, 7, vcc
	v_cmp_eq_u32_e32 vcc, 42, v156
	s_and_saveexec_b64 s[6:7], vcc
	v_mov_b32_e32 v1, 8
	v_mov_b32_e32 v0, 0
	s_or_b64 s[0:1], s[0:1], exec
	s_or_b64 exec, exec, s[6:7]
	v_cmp_eq_u32_e32 vcc, 43, v156
	s_or_b64 s[0:1], vcc, s[0:1]
	s_nop 0
	v_cndmask_b32_e64 v2, v0, 0, vcc
	v_cndmask_b32_e64 v0, v1, 9, vcc
	v_cmp_eq_u32_e32 vcc, 44, v156
	s_and_saveexec_b64 s[6:7], vcc
	v_mov_b32_e32 v0, 10
	v_mov_b32_e32 v2, 0
	s_or_b64 s[0:1], s[0:1], exec
	s_or_b64 exec, exec, s[6:7]
	v_cmp_eq_u32_e32 vcc, 45, v156
	s_or_b64 s[0:1], vcc, s[0:1]
	s_nop 0
	v_cndmask_b32_e64 v2, v2, 0, vcc
	v_cndmask_b32_e64 v1, v0, 11, vcc
	v_cmp_eq_u32_e32 vcc, 46, v156
	s_and_saveexec_b64 s[6:7], vcc
	v_mov_b32_e32 v1, 12
	v_mov_b32_e32 v2, 0
	s_or_b64 s[0:1], s[0:1], exec
	s_or_b64 exec, exec, s[6:7]
	v_cmp_eq_u32_e32 vcc, 47, v156
	s_or_b64 s[0:1], vcc, s[0:1]
	s_nop 0
	v_cndmask_b32_e64 v0, v2, 0, vcc
	v_cndmask_b32_e64 v2, v1, 13, vcc
	v_cmp_eq_u32_e32 vcc, 48, v156
	s_and_saveexec_b64 s[6:7], vcc
	v_mov_b32_e32 v2, 14
	v_mov_b32_e32 v0, 0
	s_or_b64 s[0:1], s[0:1], exec
	s_or_b64 exec, exec, s[6:7]
	s_andn2_b64 vcc, exec, s[84:85]
	s_cbranch_vccnz .LBB0_2802
	v_cmp_eq_u32_e32 vcc, 49, v156
	s_ashr_i32 s3, s2, 31
	s_or_b64 s[0:1], vcc, s[0:1]
	v_ashrrev_i32_e32 v34, 6, v190
	s_lshl_b64 s[6:7], s[2:3], 12
	v_ashrrev_i32_e32 v35, 31, v34
	s_add_u32 s6, s86, s6
	s_addc_u32 s7, s87, s7
	v_lshlrev_b64 v[36:37], 9, v[34:35]
	v_cndmask_b32_e64 v157, v0, 0, vcc
	v_mov_b32_e32 v33, 0
	v_lshl_add_u64 v[0:1], s[6:7], 0, v[36:37]
	v_lshlrev_b32_e32 v32, 1, v156
	v_lshl_add_u64 v[0:1], v[0:1], 0, v[32:33]
	global_load_ushort v3, v[0:1], off
	global_load_ushort v4, v[0:1], off offset:128
	v_cndmask_b32_e64 v161, v2, 15, vcc
	global_load_ushort v2, v[0:1], off offset:256
	global_load_ushort v5, v[0:1], off offset:384
	v_mov_b32_e32 v158, 0xffffff00
	v_bfrev_b32_e32 v159, 1
	s_movk_i32 s54, 0xff
	v_or_b32_e32 v160, 64, v156
	s_movk_i32 s33, 0xff00
	s_waitcnt vmcnt(3)
	v_lshlrev_b32_e32 v0, 16, v3
	s_waitcnt vmcnt(2)
	v_lshlrev_b32_e32 v1, 16, v4
	v_cmp_lt_i32_e32 vcc, -1, v0
	s_nop 1
	v_cndmask_b32_e32 v3, v158, v159, vcc
	v_cmp_lt_i32_e32 vcc, -1, v1
	v_xor_b32_e32 v0, v3, v0
	v_bitop3_b32 v0, v0, s54, v156 bitop3:0x36
	v_cndmask_b32_e32 v4, v158, v159, vcc
	v_xor_b32_e32 v1, v4, v1
	v_bitop3_b32 v1, v1, s54, v160 bitop3:0x36
	v_max_u32_e32 v3, v0, v1
	s_nop 1
	v_max_u32_dpp v3, v3, v3 quad_perm:[1,0,3,2] row_mask:0xf bank_mask:0xf bound_ctrl:1
	s_nop 1
	v_max_u32_dpp v3, v3, v3 quad_perm:[2,3,0,1] row_mask:0xf bank_mask:0xf bound_ctrl:1
	s_nop 1
	v_max_u32_dpp v3, v3, v3 row_half_mirror row_mask:0xf bank_mask:0xf bound_ctrl:1
	s_nop 1
	v_max_u32_dpp v3, v3, v3 row_mirror row_mask:0xf bank_mask:0xf bound_ctrl:1
	s_nop 0
	v_readlane_b32 s7, v3, 32
	v_readlane_b32 s8, v3, 48
	v_readlane_b32 s6, v3, 16
	s_max_u32 s7, s7, s8
	v_readlane_b32 s3, v3, 0
	v_mov_b32_e32 v3, s6
	v_mov_b32_e32 v4, s7
	v_max3_u32 v3, s3, v3, v4
	v_cmp_ne_u32_e32 vcc, v0, v3
	v_cmp_eq_u32_e64 s[6:7], 0, v156
	s_nop 0
	v_cndmask_b32_e32 v0, 0, v0, vcc
	v_cmp_ne_u32_e32 vcc, v1, v3
	v_cndmask_b32_e64 v3, 0, v3, s[6:7]
	s_nop 0
	v_cndmask_b32_e32 v1, 0, v1, vcc
	v_max_u32_e32 v4, v0, v1
	s_nop 1
	v_max_u32_dpp v4, v4, v4 quad_perm:[1,0,3,2] row_mask:0xf bank_mask:0xf bound_ctrl:1
	s_nop 1
	v_max_u32_dpp v4, v4, v4 quad_perm:[2,3,0,1] row_mask:0xf bank_mask:0xf bound_ctrl:1
	s_nop 1
	v_max_u32_dpp v4, v4, v4 row_half_mirror row_mask:0xf bank_mask:0xf bound_ctrl:1
	s_nop 1
	v_max_u32_dpp v4, v4, v4 row_mirror row_mask:0xf bank_mask:0xf bound_ctrl:1
	s_nop 0
	v_readlane_b32 s9, v4, 32
	v_readlane_b32 s10, v4, 48
	v_readlane_b32 s8, v4, 16
	s_max_u32 s9, s9, s10
	v_readlane_b32 s3, v4, 0
	v_mov_b32_e32 v4, s8
	v_mov_b32_e32 v6, s9
	v_max3_u32 v4, s3, v4, v6
	v_cmp_ne_u32_e32 vcc, v0, v4
	v_cmp_eq_u32_e64 s[8:9], 1, v156
	s_nop 0
	v_cndmask_b32_e32 v0, 0, v0, vcc
	v_cmp_ne_u32_e32 vcc, v1, v4
	v_cndmask_b32_e64 v3, v3, v4, s[8:9]
	s_nop 0
	v_cndmask_b32_e32 v1, 0, v1, vcc
	v_max_u32_e32 v4, v0, v1
	s_nop 1
	v_max_u32_dpp v4, v4, v4 quad_perm:[1,0,3,2] row_mask:0xf bank_mask:0xf bound_ctrl:1
	s_nop 1
	v_max_u32_dpp v4, v4, v4 quad_perm:[2,3,0,1] row_mask:0xf bank_mask:0xf bound_ctrl:1
	s_nop 1
	v_max_u32_dpp v4, v4, v4 row_half_mirror row_mask:0xf bank_mask:0xf bound_ctrl:1
	s_nop 1
	v_max_u32_dpp v4, v4, v4 row_mirror row_mask:0xf bank_mask:0xf bound_ctrl:1
	s_nop 0
	v_readlane_b32 s11, v4, 32
	v_readlane_b32 s12, v4, 48
	v_readlane_b32 s10, v4, 16
	s_max_u32 s11, s11, s12
	v_readlane_b32 s3, v4, 0
	v_mov_b32_e32 v4, s10
	v_mov_b32_e32 v6, s11
	v_max3_u32 v4, s3, v4, v6
	v_cmp_ne_u32_e32 vcc, v0, v4
	v_cmp_eq_u32_e64 s[10:11], 2, v156
	s_nop 0
	v_cndmask_b32_e32 v0, 0, v0, vcc
	v_cmp_ne_u32_e32 vcc, v1, v4
	v_cndmask_b32_e64 v3, v3, v4, s[10:11]
	s_nop 0
	v_cndmask_b32_e32 v1, 0, v1, vcc
	v_max_u32_e32 v4, v0, v1
	s_nop 1
	v_max_u32_dpp v4, v4, v4 quad_perm:[1,0,3,2] row_mask:0xf bank_mask:0xf bound_ctrl:1
	s_nop 1
	v_max_u32_dpp v4, v4, v4 quad_perm:[2,3,0,1] row_mask:0xf bank_mask:0xf bound_ctrl:1
	s_nop 1
	v_max_u32_dpp v4, v4, v4 row_half_mirror row_mask:0xf bank_mask:0xf bound_ctrl:1
	s_nop 1
	v_max_u32_dpp v4, v4, v4 row_mirror row_mask:0xf bank_mask:0xf bound_ctrl:1
	s_nop 0
	v_readlane_b32 s13, v4, 32
	v_readlane_b32 s14, v4, 48
	v_readlane_b32 s12, v4, 16
	s_max_u32 s13, s13, s14
	v_readlane_b32 s3, v4, 0
	v_mov_b32_e32 v4, s12
	v_mov_b32_e32 v6, s13
	v_max3_u32 v4, s3, v4, v6
	v_cmp_ne_u32_e32 vcc, v0, v4
	v_cmp_eq_u32_e64 s[12:13], 3, v156
	s_nop 0
	v_cndmask_b32_e32 v0, 0, v0, vcc
	v_cmp_ne_u32_e32 vcc, v1, v4
	v_cndmask_b32_e64 v3, v3, v4, s[12:13]
	s_nop 0
	v_cndmask_b32_e32 v1, 0, v1, vcc
	v_max_u32_e32 v4, v0, v1
	s_nop 1
	v_max_u32_dpp v4, v4, v4 quad_perm:[1,0,3,2] row_mask:0xf bank_mask:0xf bound_ctrl:1
	s_nop 1
	v_max_u32_dpp v4, v4, v4 quad_perm:[2,3,0,1] row_mask:0xf bank_mask:0xf bound_ctrl:1
	s_nop 1
	v_max_u32_dpp v4, v4, v4 row_half_mirror row_mask:0xf bank_mask:0xf bound_ctrl:1
	s_nop 1
	v_max_u32_dpp v4, v4, v4 row_mirror row_mask:0xf bank_mask:0xf bound_ctrl:1
	s_nop 0
	v_readlane_b32 s15, v4, 32
	v_readlane_b32 s16, v4, 48
	v_readlane_b32 s14, v4, 16
	s_max_u32 s15, s15, s16
	v_readlane_b32 s3, v4, 0
	v_mov_b32_e32 v4, s14
	v_mov_b32_e32 v6, s15
	v_max3_u32 v4, s3, v4, v6
	v_cmp_ne_u32_e32 vcc, v0, v4
	v_cmp_eq_u32_e64 s[14:15], 4, v156
	s_nop 0
	v_cndmask_b32_e32 v0, 0, v0, vcc
	v_cmp_ne_u32_e32 vcc, v1, v4
	v_cndmask_b32_e64 v3, v3, v4, s[14:15]
	s_nop 0
	v_cndmask_b32_e32 v1, 0, v1, vcc
	v_max_u32_e32 v4, v0, v1
	s_nop 1
	v_max_u32_dpp v4, v4, v4 quad_perm:[1,0,3,2] row_mask:0xf bank_mask:0xf bound_ctrl:1
	s_nop 1
	v_max_u32_dpp v4, v4, v4 quad_perm:[2,3,0,1] row_mask:0xf bank_mask:0xf bound_ctrl:1
	s_nop 1
	v_max_u32_dpp v4, v4, v4 row_half_mirror row_mask:0xf bank_mask:0xf bound_ctrl:1
	s_nop 1
	v_max_u32_dpp v4, v4, v4 row_mirror row_mask:0xf bank_mask:0xf bound_ctrl:1
	s_nop 0
	v_readlane_b32 s17, v4, 32
	v_readlane_b32 s18, v4, 48
	v_readlane_b32 s16, v4, 16
	s_max_u32 s17, s17, s18
	v_readlane_b32 s3, v4, 0
	v_mov_b32_e32 v4, s16
	v_mov_b32_e32 v6, s17
	v_max3_u32 v4, s3, v4, v6
	v_cmp_ne_u32_e32 vcc, v0, v4
	v_cmp_eq_u32_e64 s[16:17], 5, v156
	s_nop 0
	v_cndmask_b32_e32 v0, 0, v0, vcc
	v_cmp_ne_u32_e32 vcc, v1, v4
	v_cndmask_b32_e64 v3, v3, v4, s[16:17]
	s_nop 0
	v_cndmask_b32_e32 v1, 0, v1, vcc
	v_max_u32_e32 v4, v0, v1
	s_nop 1
	v_max_u32_dpp v4, v4, v4 quad_perm:[1,0,3,2] row_mask:0xf bank_mask:0xf bound_ctrl:1
	s_nop 1
	v_max_u32_dpp v4, v4, v4 quad_perm:[2,3,0,1] row_mask:0xf bank_mask:0xf bound_ctrl:1
	s_nop 1
	v_max_u32_dpp v4, v4, v4 row_half_mirror row_mask:0xf bank_mask:0xf bound_ctrl:1
	s_nop 1
	v_max_u32_dpp v4, v4, v4 row_mirror row_mask:0xf bank_mask:0xf bound_ctrl:1
	s_nop 0
	v_readlane_b32 s19, v4, 32
	v_readlane_b32 s20, v4, 48
	v_readlane_b32 s18, v4, 16
	s_max_u32 s19, s19, s20
	v_readlane_b32 s3, v4, 0
	v_mov_b32_e32 v4, s18
	v_mov_b32_e32 v6, s19
	v_max3_u32 v4, s3, v4, v6
	v_cmp_ne_u32_e32 vcc, v0, v4
	v_cmp_eq_u32_e64 s[18:19], 6, v156
	s_nop 0
	v_cndmask_b32_e32 v0, 0, v0, vcc
	v_cmp_ne_u32_e32 vcc, v1, v4
	v_cndmask_b32_e64 v3, v3, v4, s[18:19]
	s_nop 0
	v_cndmask_b32_e32 v1, 0, v1, vcc
	v_max_u32_e32 v4, v0, v1
	s_nop 1
	v_max_u32_dpp v4, v4, v4 quad_perm:[1,0,3,2] row_mask:0xf bank_mask:0xf bound_ctrl:1
	s_nop 1
	v_max_u32_dpp v4, v4, v4 quad_perm:[2,3,0,1] row_mask:0xf bank_mask:0xf bound_ctrl:1
	s_nop 1
	v_max_u32_dpp v4, v4, v4 row_half_mirror row_mask:0xf bank_mask:0xf bound_ctrl:1
	s_nop 1
	v_max_u32_dpp v4, v4, v4 row_mirror row_mask:0xf bank_mask:0xf bound_ctrl:1
	s_nop 0
	v_readlane_b32 s21, v4, 32
	v_readlane_b32 s22, v4, 48
	v_readlane_b32 s20, v4, 16
	s_max_u32 s21, s21, s22
	v_readlane_b32 s3, v4, 0
	v_mov_b32_e32 v4, s20
	v_mov_b32_e32 v6, s21
	v_max3_u32 v4, s3, v4, v6
	v_cmp_ne_u32_e32 vcc, v0, v4
	v_cmp_eq_u32_e64 s[20:21], 7, v156
	s_nop 0
	v_cndmask_b32_e32 v0, 0, v0, vcc
	v_cmp_ne_u32_e32 vcc, v1, v4
	v_cndmask_b32_e64 v3, v3, v4, s[20:21]
	s_nop 0
	v_cndmask_b32_e32 v1, 0, v1, vcc
	v_max_u32_e32 v4, v0, v1
	s_nop 1
	v_max_u32_dpp v4, v4, v4 quad_perm:[1,0,3,2] row_mask:0xf bank_mask:0xf bound_ctrl:1
	s_nop 1
	v_max_u32_dpp v4, v4, v4 quad_perm:[2,3,0,1] row_mask:0xf bank_mask:0xf bound_ctrl:1
	s_nop 1
	v_max_u32_dpp v4, v4, v4 row_half_mirror row_mask:0xf bank_mask:0xf bound_ctrl:1
	s_nop 1
	v_max_u32_dpp v4, v4, v4 row_mirror row_mask:0xf bank_mask:0xf bound_ctrl:1
	s_nop 0
	v_readlane_b32 s23, v4, 32
	v_readlane_b32 s24, v4, 48
	v_readlane_b32 s22, v4, 16
	s_max_u32 s23, s23, s24
	v_readlane_b32 s3, v4, 0
	v_mov_b32_e32 v4, s22
	v_mov_b32_e32 v6, s23
	v_max3_u32 v4, s3, v4, v6
	v_cmp_ne_u32_e32 vcc, v0, v4
	v_cmp_eq_u32_e64 s[22:23], 8, v156
	s_nop 0
	v_cndmask_b32_e32 v0, 0, v0, vcc
	v_cmp_ne_u32_e32 vcc, v1, v4
	v_cndmask_b32_e64 v3, v3, v4, s[22:23]
	s_nop 0
	v_cndmask_b32_e32 v1, 0, v1, vcc
	v_max_u32_e32 v4, v0, v1
	s_nop 1
	v_max_u32_dpp v4, v4, v4 quad_perm:[1,0,3,2] row_mask:0xf bank_mask:0xf bound_ctrl:1
	s_nop 1
	v_max_u32_dpp v4, v4, v4 quad_perm:[2,3,0,1] row_mask:0xf bank_mask:0xf bound_ctrl:1
	s_nop 1
	v_max_u32_dpp v4, v4, v4 row_half_mirror row_mask:0xf bank_mask:0xf bound_ctrl:1
	s_nop 1
	v_max_u32_dpp v4, v4, v4 row_mirror row_mask:0xf bank_mask:0xf bound_ctrl:1
	s_nop 0
	v_readlane_b32 s25, v4, 32
	v_readlane_b32 s26, v4, 48
	v_readlane_b32 s24, v4, 16
	s_max_u32 s25, s25, s26
	v_readlane_b32 s3, v4, 0
	v_mov_b32_e32 v4, s24
	v_mov_b32_e32 v6, s25
	v_max3_u32 v4, s3, v4, v6
	v_cmp_ne_u32_e32 vcc, v0, v4
	v_cmp_eq_u32_e64 s[24:25], 9, v156
	s_nop 0
	v_cndmask_b32_e32 v0, 0, v0, vcc
	v_cmp_ne_u32_e32 vcc, v1, v4
	v_cndmask_b32_e64 v3, v3, v4, s[24:25]
	s_nop 0
	v_cndmask_b32_e32 v1, 0, v1, vcc
	v_max_u32_e32 v4, v0, v1
	s_nop 1
	v_max_u32_dpp v4, v4, v4 quad_perm:[1,0,3,2] row_mask:0xf bank_mask:0xf bound_ctrl:1
	s_nop 1
	v_max_u32_dpp v4, v4, v4 quad_perm:[2,3,0,1] row_mask:0xf bank_mask:0xf bound_ctrl:1
	s_nop 1
	v_max_u32_dpp v4, v4, v4 row_half_mirror row_mask:0xf bank_mask:0xf bound_ctrl:1
	s_nop 1
	v_max_u32_dpp v4, v4, v4 row_mirror row_mask:0xf bank_mask:0xf bound_ctrl:1
	s_nop 0
	v_readlane_b32 s27, v4, 32
	v_readlane_b32 s28, v4, 48
	v_readlane_b32 s26, v4, 16
	s_max_u32 s27, s27, s28
	v_readlane_b32 s3, v4, 0
	v_mov_b32_e32 v4, s26
	v_mov_b32_e32 v6, s27
	v_max3_u32 v4, s3, v4, v6
	v_cmp_ne_u32_e32 vcc, v0, v4
	v_cmp_eq_u32_e64 s[26:27], 10, v156
	s_nop 0
	v_cndmask_b32_e32 v0, 0, v0, vcc
	v_cmp_ne_u32_e32 vcc, v1, v4
	v_cndmask_b32_e64 v3, v3, v4, s[26:27]
	s_nop 0
	v_cndmask_b32_e32 v1, 0, v1, vcc
	v_max_u32_e32 v4, v0, v1
	s_nop 1
	v_max_u32_dpp v4, v4, v4 quad_perm:[1,0,3,2] row_mask:0xf bank_mask:0xf bound_ctrl:1
	s_nop 1
	v_max_u32_dpp v4, v4, v4 quad_perm:[2,3,0,1] row_mask:0xf bank_mask:0xf bound_ctrl:1
	s_nop 1
	v_max_u32_dpp v4, v4, v4 row_half_mirror row_mask:0xf bank_mask:0xf bound_ctrl:1
	s_nop 1
	v_max_u32_dpp v4, v4, v4 row_mirror row_mask:0xf bank_mask:0xf bound_ctrl:1
	s_nop 0
	v_readlane_b32 s29, v4, 32
	v_readlane_b32 s30, v4, 48
	v_readlane_b32 s28, v4, 16
	s_max_u32 s29, s29, s30
	v_readlane_b32 s3, v4, 0
	v_mov_b32_e32 v4, s28
	v_mov_b32_e32 v6, s29
	v_max3_u32 v4, s3, v4, v6
	v_cmp_ne_u32_e32 vcc, v0, v4
	v_cmp_eq_u32_e64 s[28:29], 11, v156
	s_nop 0
	v_cndmask_b32_e32 v0, 0, v0, vcc
	v_cmp_ne_u32_e32 vcc, v1, v4
	v_cndmask_b32_e64 v3, v3, v4, s[28:29]
	s_nop 0
	v_cndmask_b32_e32 v1, 0, v1, vcc
	v_max_u32_e32 v4, v0, v1
	s_nop 1
	v_max_u32_dpp v4, v4, v4 quad_perm:[1,0,3,2] row_mask:0xf bank_mask:0xf bound_ctrl:1
	s_nop 1
	v_max_u32_dpp v4, v4, v4 quad_perm:[2,3,0,1] row_mask:0xf bank_mask:0xf bound_ctrl:1
	s_nop 1
	v_max_u32_dpp v4, v4, v4 row_half_mirror row_mask:0xf bank_mask:0xf bound_ctrl:1
	s_nop 1
	v_max_u32_dpp v4, v4, v4 row_mirror row_mask:0xf bank_mask:0xf bound_ctrl:1
	s_nop 0
	v_readlane_b32 s31, v4, 32
	v_readlane_b32 s34, v4, 48
	v_readlane_b32 s30, v4, 16
	s_max_u32 s31, s31, s34
	v_readlane_b32 s3, v4, 0
	v_mov_b32_e32 v4, s30
	v_mov_b32_e32 v6, s31
	v_max3_u32 v4, s3, v4, v6
	v_cmp_ne_u32_e32 vcc, v0, v4
	v_cmp_eq_u32_e64 s[30:31], 12, v156
	s_nop 0
	v_cndmask_b32_e32 v0, 0, v0, vcc
	v_cmp_ne_u32_e32 vcc, v1, v4
	v_cndmask_b32_e64 v3, v3, v4, s[30:31]
	s_nop 0
	v_cndmask_b32_e32 v1, 0, v1, vcc
	v_max_u32_e32 v4, v0, v1
	s_nop 1
	v_max_u32_dpp v4, v4, v4 quad_perm:[1,0,3,2] row_mask:0xf bank_mask:0xf bound_ctrl:1
	s_nop 1
	v_max_u32_dpp v4, v4, v4 quad_perm:[2,3,0,1] row_mask:0xf bank_mask:0xf bound_ctrl:1
	s_nop 1
	v_max_u32_dpp v4, v4, v4 row_half_mirror row_mask:0xf bank_mask:0xf bound_ctrl:1
	s_nop 1
	v_max_u32_dpp v4, v4, v4 row_mirror row_mask:0xf bank_mask:0xf bound_ctrl:1
	s_nop 0
	v_readlane_b32 s35, v4, 32
	v_readlane_b32 s36, v4, 48
	v_readlane_b32 s34, v4, 16
	s_max_u32 s35, s35, s36
	v_readlane_b32 s3, v4, 0
	v_mov_b32_e32 v4, s34
	v_mov_b32_e32 v6, s35
	v_max3_u32 v4, s3, v4, v6
	v_cmp_ne_u32_e32 vcc, v0, v4
	v_cmp_eq_u32_e64 s[34:35], 13, v156
	s_nop 0
	v_cndmask_b32_e32 v0, 0, v0, vcc
	v_cmp_ne_u32_e32 vcc, v1, v4
	v_cndmask_b32_e64 v3, v3, v4, s[34:35]
	s_nop 0
	v_cndmask_b32_e32 v1, 0, v1, vcc
	v_max_u32_e32 v4, v0, v1
	s_nop 1
	v_max_u32_dpp v4, v4, v4 quad_perm:[1,0,3,2] row_mask:0xf bank_mask:0xf bound_ctrl:1
	s_nop 1
	v_max_u32_dpp v4, v4, v4 quad_perm:[2,3,0,1] row_mask:0xf bank_mask:0xf bound_ctrl:1
	s_nop 1
	v_max_u32_dpp v4, v4, v4 row_half_mirror row_mask:0xf bank_mask:0xf bound_ctrl:1
	s_nop 1
	v_max_u32_dpp v4, v4, v4 row_mirror row_mask:0xf bank_mask:0xf bound_ctrl:1
	s_nop 0
	v_readlane_b32 s37, v4, 32
	v_readlane_b32 s38, v4, 48
	v_readlane_b32 s36, v4, 16
	s_max_u32 s37, s37, s38
	v_readlane_b32 s3, v4, 0
	v_mov_b32_e32 v4, s36
	v_mov_b32_e32 v6, s37
	v_max3_u32 v4, s3, v4, v6
	v_cmp_ne_u32_e32 vcc, v1, v4
	v_cmp_eq_u32_e64 s[36:37], 14, v156
	s_nop 0
	v_cndmask_b32_e32 v1, 0, v1, vcc
	v_max_u32_e32 v6, v0, v1
	v_cmp_eq_u32_e32 vcc, v0, v4
	v_cndmask_b32_e64 v3, v3, v4, s[36:37]
	s_nop 0
	v_cndmask_b32_e32 v0, v6, v1, vcc
	s_nop 1
	v_max_u32_dpp v0, v0, v0 quad_perm:[1,0,3,2] row_mask:0xf bank_mask:0xf bound_ctrl:1
	s_nop 1
	v_max_u32_dpp v0, v0, v0 quad_perm:[2,3,0,1] row_mask:0xf bank_mask:0xf bound_ctrl:1
	s_nop 1
	v_max_u32_dpp v0, v0, v0 row_half_mirror row_mask:0xf bank_mask:0xf bound_ctrl:1
	s_nop 1
	v_max_u32_dpp v0, v0, v0 row_mirror row_mask:0xf bank_mask:0xf bound_ctrl:1
	s_nop 0
	v_readlane_b32 s39, v0, 32
	v_readlane_b32 s40, v0, 48
	v_readlane_b32 s38, v0, 16
	s_max_u32 s39, s39, s40
	v_readlane_b32 s3, v0, 0
	v_mov_b32_e32 v0, s38
	v_mov_b32_e32 v1, s39
	v_max3_u32 v0, s3, v0, v1
	s_waitcnt vmcnt(1)
	v_lshlrev_b32_e32 v1, 16, v2
	v_cmp_lt_i32_e32 vcc, -1, v1
	v_cmp_eq_u32_e64 s[38:39], 15, v156
	s_nop 0
	v_cndmask_b32_e32 v2, v158, v159, vcc
	v_xor_b32_e32 v1, v2, v1
	s_waitcnt vmcnt(0)
	v_lshlrev_b32_e32 v2, 16, v5
	v_cmp_lt_i32_e32 vcc, -1, v2
	v_cndmask_b32_e64 v0, v3, v0, s[38:39]
	v_bitop3_b32 v1, v1, s54, v156 bitop3:0x36
	v_cndmask_b32_e32 v3, v158, v159, vcc
	v_xor_b32_e32 v2, v3, v2
	v_bitop3_b32 v2, v2, s54, v160 bitop3:0x36
	v_max_u32_e32 v3, v1, v2
	s_nop 1
	v_max_u32_dpp v3, v3, v3 quad_perm:[1,0,3,2] row_mask:0xf bank_mask:0xf bound_ctrl:1
	s_nop 1
	v_max_u32_dpp v3, v3, v3 quad_perm:[2,3,0,1] row_mask:0xf bank_mask:0xf bound_ctrl:1
	s_nop 1
	v_max_u32_dpp v3, v3, v3 row_half_mirror row_mask:0xf bank_mask:0xf bound_ctrl:1
	s_nop 1
	v_max_u32_dpp v3, v3, v3 row_mirror row_mask:0xf bank_mask:0xf bound_ctrl:1
	s_nop 0
	v_readlane_b32 s41, v3, 32
	v_readlane_b32 s42, v3, 48
	v_readlane_b32 s40, v3, 16
	s_max_u32 s41, s41, s42
	v_readlane_b32 s3, v3, 0
	v_mov_b32_e32 v3, s40
	v_mov_b32_e32 v4, s41
	v_max3_u32 v3, s3, v3, v4
	v_cmp_ne_u32_e32 vcc, v1, v3
	s_nop 1
	v_cndmask_b32_e32 v1, 0, v1, vcc
	v_cmp_ne_u32_e32 vcc, v2, v3
	v_cndmask_b32_e64 v3, 0, v3, s[6:7]
	s_nop 0
	v_cndmask_b32_e32 v2, 0, v2, vcc
	v_max_u32_e32 v4, v1, v2
	s_nop 1
	v_max_u32_dpp v4, v4, v4 quad_perm:[1,0,3,2] row_mask:0xf bank_mask:0xf bound_ctrl:1
	s_nop 1
	v_max_u32_dpp v4, v4, v4 quad_perm:[2,3,0,1] row_mask:0xf bank_mask:0xf bound_ctrl:1
	s_nop 1
	v_max_u32_dpp v4, v4, v4 row_half_mirror row_mask:0xf bank_mask:0xf bound_ctrl:1
	s_nop 1
	v_max_u32_dpp v4, v4, v4 row_mirror row_mask:0xf bank_mask:0xf bound_ctrl:1
	s_nop 0
	v_readlane_b32 s41, v4, 32
	v_readlane_b32 s42, v4, 48
	v_readlane_b32 s40, v4, 16
	s_max_u32 s41, s41, s42
	v_readlane_b32 s3, v4, 0
	v_mov_b32_e32 v4, s40
	v_mov_b32_e32 v5, s41
	v_max3_u32 v4, s3, v4, v5
	v_cmp_ne_u32_e32 vcc, v1, v4
	v_cndmask_b32_e64 v3, v3, v4, s[8:9]
	s_nop 0
	v_cndmask_b32_e32 v1, 0, v1, vcc
	v_cmp_ne_u32_e32 vcc, v2, v4
	s_nop 1
	v_cndmask_b32_e32 v2, 0, v2, vcc
	v_max_u32_e32 v4, v1, v2
	s_nop 1
	v_max_u32_dpp v4, v4, v4 quad_perm:[1,0,3,2] row_mask:0xf bank_mask:0xf bound_ctrl:1
	s_nop 1
	v_max_u32_dpp v4, v4, v4 quad_perm:[2,3,0,1] row_mask:0xf bank_mask:0xf bound_ctrl:1
	s_nop 1
	v_max_u32_dpp v4, v4, v4 row_half_mirror row_mask:0xf bank_mask:0xf bound_ctrl:1
	s_nop 1
	v_max_u32_dpp v4, v4, v4 row_mirror row_mask:0xf bank_mask:0xf bound_ctrl:1
	s_nop 0
	v_readlane_b32 s41, v4, 32
	v_readlane_b32 s42, v4, 48
	v_readlane_b32 s40, v4, 16
	s_max_u32 s41, s41, s42
	v_readlane_b32 s3, v4, 0
	v_mov_b32_e32 v4, s40
	v_mov_b32_e32 v5, s41
	v_max3_u32 v4, s3, v4, v5
	v_cmp_ne_u32_e32 vcc, v1, v4
	v_cndmask_b32_e64 v3, v3, v4, s[10:11]
	s_nop 0
	v_cndmask_b32_e32 v1, 0, v1, vcc
	v_cmp_ne_u32_e32 vcc, v2, v4
	s_nop 1
	v_cndmask_b32_e32 v2, 0, v2, vcc
	v_max_u32_e32 v4, v1, v2
	s_nop 1
	v_max_u32_dpp v4, v4, v4 quad_perm:[1,0,3,2] row_mask:0xf bank_mask:0xf bound_ctrl:1
	s_nop 1
	v_max_u32_dpp v4, v4, v4 quad_perm:[2,3,0,1] row_mask:0xf bank_mask:0xf bound_ctrl:1
	s_nop 1
	v_max_u32_dpp v4, v4, v4 row_half_mirror row_mask:0xf bank_mask:0xf bound_ctrl:1
	s_nop 1
	v_max_u32_dpp v4, v4, v4 row_mirror row_mask:0xf bank_mask:0xf bound_ctrl:1
	s_nop 0
	v_readlane_b32 s41, v4, 32
	v_readlane_b32 s42, v4, 48
	v_readlane_b32 s40, v4, 16
	s_max_u32 s41, s41, s42
	v_readlane_b32 s3, v4, 0
	v_mov_b32_e32 v4, s40
	v_mov_b32_e32 v5, s41
	v_max3_u32 v4, s3, v4, v5
	v_cmp_ne_u32_e32 vcc, v1, v4
	v_cndmask_b32_e64 v3, v3, v4, s[12:13]
	s_nop 0
	v_cndmask_b32_e32 v1, 0, v1, vcc
	v_cmp_ne_u32_e32 vcc, v2, v4
	s_nop 1
	v_cndmask_b32_e32 v2, 0, v2, vcc
	v_max_u32_e32 v4, v1, v2
	s_nop 1
	v_max_u32_dpp v4, v4, v4 quad_perm:[1,0,3,2] row_mask:0xf bank_mask:0xf bound_ctrl:1
	s_nop 1
	v_max_u32_dpp v4, v4, v4 quad_perm:[2,3,0,1] row_mask:0xf bank_mask:0xf bound_ctrl:1
	s_nop 1
	v_max_u32_dpp v4, v4, v4 row_half_mirror row_mask:0xf bank_mask:0xf bound_ctrl:1
	s_nop 1
	v_max_u32_dpp v4, v4, v4 row_mirror row_mask:0xf bank_mask:0xf bound_ctrl:1
	s_nop 0
	v_readlane_b32 s41, v4, 32
	v_readlane_b32 s42, v4, 48
	v_readlane_b32 s40, v4, 16
	s_max_u32 s41, s41, s42
	v_readlane_b32 s3, v4, 0
	v_mov_b32_e32 v4, s40
	v_mov_b32_e32 v5, s41
	v_max3_u32 v4, s3, v4, v5
	v_cmp_ne_u32_e32 vcc, v1, v4
	v_cndmask_b32_e64 v3, v3, v4, s[14:15]
	s_nop 0
	v_cndmask_b32_e32 v1, 0, v1, vcc
	v_cmp_ne_u32_e32 vcc, v2, v4
	s_nop 1
	v_cndmask_b32_e32 v2, 0, v2, vcc
	v_max_u32_e32 v4, v1, v2
	s_nop 1
	v_max_u32_dpp v4, v4, v4 quad_perm:[1,0,3,2] row_mask:0xf bank_mask:0xf bound_ctrl:1
	s_nop 1
	v_max_u32_dpp v4, v4, v4 quad_perm:[2,3,0,1] row_mask:0xf bank_mask:0xf bound_ctrl:1
	s_nop 1
	v_max_u32_dpp v4, v4, v4 row_half_mirror row_mask:0xf bank_mask:0xf bound_ctrl:1
	s_nop 1
	v_max_u32_dpp v4, v4, v4 row_mirror row_mask:0xf bank_mask:0xf bound_ctrl:1
	s_nop 0
	v_readlane_b32 s41, v4, 32
	v_readlane_b32 s42, v4, 48
	v_readlane_b32 s40, v4, 16
	s_max_u32 s41, s41, s42
	v_readlane_b32 s3, v4, 0
	v_mov_b32_e32 v4, s40
	v_mov_b32_e32 v5, s41
	v_max3_u32 v4, s3, v4, v5
	v_cmp_ne_u32_e32 vcc, v1, v4
	v_cndmask_b32_e64 v3, v3, v4, s[16:17]
	s_nop 0
	v_cndmask_b32_e32 v1, 0, v1, vcc
	v_cmp_ne_u32_e32 vcc, v2, v4
	s_nop 1
	v_cndmask_b32_e32 v2, 0, v2, vcc
	v_max_u32_e32 v4, v1, v2
	s_nop 1
	v_max_u32_dpp v4, v4, v4 quad_perm:[1,0,3,2] row_mask:0xf bank_mask:0xf bound_ctrl:1
	s_nop 1
	v_max_u32_dpp v4, v4, v4 quad_perm:[2,3,0,1] row_mask:0xf bank_mask:0xf bound_ctrl:1
	s_nop 1
	v_max_u32_dpp v4, v4, v4 row_half_mirror row_mask:0xf bank_mask:0xf bound_ctrl:1
	s_nop 1
	v_max_u32_dpp v4, v4, v4 row_mirror row_mask:0xf bank_mask:0xf bound_ctrl:1
	s_nop 0
	v_readlane_b32 s41, v4, 32
	v_readlane_b32 s42, v4, 48
	v_readlane_b32 s40, v4, 16
	s_max_u32 s41, s41, s42
	v_readlane_b32 s3, v4, 0
	v_mov_b32_e32 v4, s40
	v_mov_b32_e32 v5, s41
	v_max3_u32 v4, s3, v4, v5
	v_cmp_ne_u32_e32 vcc, v1, v4
	v_cndmask_b32_e64 v3, v3, v4, s[18:19]
	s_nop 0
	v_cndmask_b32_e32 v1, 0, v1, vcc
	v_cmp_ne_u32_e32 vcc, v2, v4
	s_nop 1
	v_cndmask_b32_e32 v2, 0, v2, vcc
	v_max_u32_e32 v4, v1, v2
	s_nop 1
	v_max_u32_dpp v4, v4, v4 quad_perm:[1,0,3,2] row_mask:0xf bank_mask:0xf bound_ctrl:1
	s_nop 1
	v_max_u32_dpp v4, v4, v4 quad_perm:[2,3,0,1] row_mask:0xf bank_mask:0xf bound_ctrl:1
	s_nop 1
	v_max_u32_dpp v4, v4, v4 row_half_mirror row_mask:0xf bank_mask:0xf bound_ctrl:1
	s_nop 1
	v_max_u32_dpp v4, v4, v4 row_mirror row_mask:0xf bank_mask:0xf bound_ctrl:1
	s_nop 0
	v_readlane_b32 s41, v4, 32
	v_readlane_b32 s42, v4, 48
	v_readlane_b32 s40, v4, 16
	s_max_u32 s41, s41, s42
	v_readlane_b32 s3, v4, 0
	v_mov_b32_e32 v4, s40
	v_mov_b32_e32 v5, s41
	v_max3_u32 v4, s3, v4, v5
	v_cmp_ne_u32_e32 vcc, v1, v4
	v_cndmask_b32_e64 v3, v3, v4, s[20:21]
	s_nop 0
	v_cndmask_b32_e32 v1, 0, v1, vcc
	v_cmp_ne_u32_e32 vcc, v2, v4
	s_nop 1
	v_cndmask_b32_e32 v2, 0, v2, vcc
	v_max_u32_e32 v4, v1, v2
	s_nop 1
	v_max_u32_dpp v4, v4, v4 quad_perm:[1,0,3,2] row_mask:0xf bank_mask:0xf bound_ctrl:1
	s_nop 1
	v_max_u32_dpp v4, v4, v4 quad_perm:[2,3,0,1] row_mask:0xf bank_mask:0xf bound_ctrl:1
	s_nop 1
	v_max_u32_dpp v4, v4, v4 row_half_mirror row_mask:0xf bank_mask:0xf bound_ctrl:1
	s_nop 1
	v_max_u32_dpp v4, v4, v4 row_mirror row_mask:0xf bank_mask:0xf bound_ctrl:1
	s_nop 0
	v_readlane_b32 s41, v4, 32
	v_readlane_b32 s42, v4, 48
	v_readlane_b32 s40, v4, 16
	s_max_u32 s41, s41, s42
	v_readlane_b32 s3, v4, 0
	v_mov_b32_e32 v4, s40
	v_mov_b32_e32 v5, s41
	v_max3_u32 v4, s3, v4, v5
	v_cmp_ne_u32_e32 vcc, v1, v4
	v_cndmask_b32_e64 v3, v3, v4, s[22:23]
	s_nop 0
	v_cndmask_b32_e32 v1, 0, v1, vcc
	v_cmp_ne_u32_e32 vcc, v2, v4
	s_nop 1
	v_cndmask_b32_e32 v2, 0, v2, vcc
	v_max_u32_e32 v4, v1, v2
	s_nop 1
	v_max_u32_dpp v4, v4, v4 quad_perm:[1,0,3,2] row_mask:0xf bank_mask:0xf bound_ctrl:1
	s_nop 1
	v_max_u32_dpp v4, v4, v4 quad_perm:[2,3,0,1] row_mask:0xf bank_mask:0xf bound_ctrl:1
	s_nop 1
	v_max_u32_dpp v4, v4, v4 row_half_mirror row_mask:0xf bank_mask:0xf bound_ctrl:1
	s_nop 1
	v_max_u32_dpp v4, v4, v4 row_mirror row_mask:0xf bank_mask:0xf bound_ctrl:1
	s_nop 0
	v_readlane_b32 s41, v4, 32
	v_readlane_b32 s42, v4, 48
	v_readlane_b32 s40, v4, 16
	s_max_u32 s41, s41, s42
	v_readlane_b32 s3, v4, 0
	v_mov_b32_e32 v4, s40
	v_mov_b32_e32 v5, s41
	v_max3_u32 v4, s3, v4, v5
	v_cmp_ne_u32_e32 vcc, v1, v4
	v_cndmask_b32_e64 v3, v3, v4, s[24:25]
	s_nop 0
	v_cndmask_b32_e32 v1, 0, v1, vcc
	v_cmp_ne_u32_e32 vcc, v2, v4
	s_nop 1
	v_cndmask_b32_e32 v2, 0, v2, vcc
	v_max_u32_e32 v4, v1, v2
	s_nop 1
	v_max_u32_dpp v4, v4, v4 quad_perm:[1,0,3,2] row_mask:0xf bank_mask:0xf bound_ctrl:1
	s_nop 1
	v_max_u32_dpp v4, v4, v4 quad_perm:[2,3,0,1] row_mask:0xf bank_mask:0xf bound_ctrl:1
	s_nop 1
	v_max_u32_dpp v4, v4, v4 row_half_mirror row_mask:0xf bank_mask:0xf bound_ctrl:1
	s_nop 1
	v_max_u32_dpp v4, v4, v4 row_mirror row_mask:0xf bank_mask:0xf bound_ctrl:1
	s_nop 0
	v_readlane_b32 s41, v4, 32
	v_readlane_b32 s42, v4, 48
	v_readlane_b32 s40, v4, 16
	s_max_u32 s41, s41, s42
	v_readlane_b32 s3, v4, 0
	v_mov_b32_e32 v4, s40
	v_mov_b32_e32 v5, s41
	v_max3_u32 v4, s3, v4, v5
	v_cmp_ne_u32_e32 vcc, v1, v4
	v_cndmask_b32_e64 v3, v3, v4, s[26:27]
	s_nop 0
	v_cndmask_b32_e32 v1, 0, v1, vcc
	v_cmp_ne_u32_e32 vcc, v2, v4
	s_nop 1
	v_cndmask_b32_e32 v2, 0, v2, vcc
	v_max_u32_e32 v4, v1, v2
	s_nop 1
	v_max_u32_dpp v4, v4, v4 quad_perm:[1,0,3,2] row_mask:0xf bank_mask:0xf bound_ctrl:1
	s_nop 1
	v_max_u32_dpp v4, v4, v4 quad_perm:[2,3,0,1] row_mask:0xf bank_mask:0xf bound_ctrl:1
	s_nop 1
	v_max_u32_dpp v4, v4, v4 row_half_mirror row_mask:0xf bank_mask:0xf bound_ctrl:1
	s_nop 1
	v_max_u32_dpp v4, v4, v4 row_mirror row_mask:0xf bank_mask:0xf bound_ctrl:1
	s_nop 0
	v_readlane_b32 s41, v4, 32
	v_readlane_b32 s42, v4, 48
	v_readlane_b32 s40, v4, 16
	s_max_u32 s41, s41, s42
	v_readlane_b32 s3, v4, 0
	v_mov_b32_e32 v4, s40
	v_mov_b32_e32 v5, s41
	v_max3_u32 v4, s3, v4, v5
	v_cmp_ne_u32_e32 vcc, v1, v4
	v_cndmask_b32_e64 v3, v3, v4, s[28:29]
	s_nop 0
	v_cndmask_b32_e32 v1, 0, v1, vcc
	v_cmp_ne_u32_e32 vcc, v2, v4
	s_nop 1
	v_cndmask_b32_e32 v2, 0, v2, vcc
	v_max_u32_e32 v4, v1, v2
	s_nop 1
	v_max_u32_dpp v4, v4, v4 quad_perm:[1,0,3,2] row_mask:0xf bank_mask:0xf bound_ctrl:1
	s_nop 1
	v_max_u32_dpp v4, v4, v4 quad_perm:[2,3,0,1] row_mask:0xf bank_mask:0xf bound_ctrl:1
	s_nop 1
	v_max_u32_dpp v4, v4, v4 row_half_mirror row_mask:0xf bank_mask:0xf bound_ctrl:1
	s_nop 1
	v_max_u32_dpp v4, v4, v4 row_mirror row_mask:0xf bank_mask:0xf bound_ctrl:1
	s_nop 0
	v_readlane_b32 s41, v4, 32
	v_readlane_b32 s42, v4, 48
	v_readlane_b32 s40, v4, 16
	s_max_u32 s41, s41, s42
	v_readlane_b32 s3, v4, 0
	v_mov_b32_e32 v4, s40
	v_mov_b32_e32 v5, s41
	v_max3_u32 v4, s3, v4, v5
	v_cmp_ne_u32_e32 vcc, v1, v4
	v_cndmask_b32_e64 v3, v3, v4, s[30:31]
	s_nop 0
	v_cndmask_b32_e32 v1, 0, v1, vcc
	v_cmp_ne_u32_e32 vcc, v2, v4
	s_nop 1
	v_cndmask_b32_e32 v2, 0, v2, vcc
	v_max_u32_e32 v4, v1, v2
	s_nop 1
	v_max_u32_dpp v4, v4, v4 quad_perm:[1,0,3,2] row_mask:0xf bank_mask:0xf bound_ctrl:1
	s_nop 1
	v_max_u32_dpp v4, v4, v4 quad_perm:[2,3,0,1] row_mask:0xf bank_mask:0xf bound_ctrl:1
	s_nop 1
	v_max_u32_dpp v4, v4, v4 row_half_mirror row_mask:0xf bank_mask:0xf bound_ctrl:1
	s_nop 1
	v_max_u32_dpp v4, v4, v4 row_mirror row_mask:0xf bank_mask:0xf bound_ctrl:1
	s_nop 0
	v_readlane_b32 s41, v4, 32
	v_readlane_b32 s42, v4, 48
	v_readlane_b32 s40, v4, 16
	s_max_u32 s41, s41, s42
	v_readlane_b32 s3, v4, 0
	v_mov_b32_e32 v4, s40
	v_mov_b32_e32 v5, s41
	v_max3_u32 v4, s3, v4, v5
	v_cmp_ne_u32_e32 vcc, v1, v4
	v_cndmask_b32_e64 v3, v3, v4, s[34:35]
	s_nop 0
	v_cndmask_b32_e32 v1, 0, v1, vcc
	v_cmp_ne_u32_e32 vcc, v2, v4
	s_nop 1
	v_cndmask_b32_e32 v2, 0, v2, vcc
	v_max_u32_e32 v4, v1, v2
	s_nop 1
	v_max_u32_dpp v4, v4, v4 quad_perm:[1,0,3,2] row_mask:0xf bank_mask:0xf bound_ctrl:1
	s_nop 1
	v_max_u32_dpp v4, v4, v4 quad_perm:[2,3,0,1] row_mask:0xf bank_mask:0xf bound_ctrl:1
	s_nop 1
	v_max_u32_dpp v4, v4, v4 row_half_mirror row_mask:0xf bank_mask:0xf bound_ctrl:1
	s_nop 1
	v_max_u32_dpp v4, v4, v4 row_mirror row_mask:0xf bank_mask:0xf bound_ctrl:1
	s_nop 0
	v_readlane_b32 s41, v4, 32
	v_readlane_b32 s42, v4, 48
	v_readlane_b32 s40, v4, 16
	s_max_u32 s41, s41, s42
	v_readlane_b32 s3, v4, 0
	v_mov_b32_e32 v4, s40
	v_mov_b32_e32 v5, s41
	v_max3_u32 v4, s3, v4, v5
	v_cmp_ne_u32_e32 vcc, v2, v4
	v_cndmask_b32_e64 v3, v3, v4, s[36:37]
	s_nop 0
	v_cndmask_b32_e32 v2, 0, v2, vcc
	v_max_u32_e32 v5, v1, v2
	v_cmp_eq_u32_e32 vcc, v1, v4
	s_nop 1
	v_cndmask_b32_e32 v1, v5, v2, vcc
	v_cmp_lt_i32_e32 vcc, -1, v0
	s_nop 0
	v_max_u32_dpp v1, v1, v1 quad_perm:[1,0,3,2] row_mask:0xf bank_mask:0xf bound_ctrl:1
	s_nop 1
	v_max_u32_dpp v1, v1, v1 quad_perm:[2,3,0,1] row_mask:0xf bank_mask:0xf bound_ctrl:1
	s_nop 1
	v_max_u32_dpp v1, v1, v1 row_half_mirror row_mask:0xf bank_mask:0xf bound_ctrl:1
	s_nop 1
	v_max_u32_dpp v1, v1, v1 row_mirror row_mask:0xf bank_mask:0xf bound_ctrl:1
	s_nop 0
	v_readlane_b32 s41, v1, 32
	v_readlane_b32 s42, v1, 48
	v_readlane_b32 s40, v1, 16
	s_max_u32 s41, s41, s42
	v_readlane_b32 s3, v1, 0
	v_mov_b32_e32 v1, s40
	v_mov_b32_e32 v2, s41
	v_max3_u32 v1, s3, v1, v2
	v_cndmask_b32_e64 v1, v3, v1, s[38:39]
	v_cndmask_b32_e64 v2, v159, -1, vcc
	v_cmp_lt_i32_e32 vcc, -1, v1
	v_bitop3_b32 v2, v2, v0, s33 bitop3:0x78
	s_mov_b32 s41, 0
	v_cndmask_b32_e64 v3, v159, -1, vcc
	v_bitop3_b32 v4, v3, v1, s33 bitop3:0x78
	v_mbcnt_hi_u32_b32 v3, -1, v191
	v_and_b32_e32 v162, 64, v3
	v_or_b32_e32 v3, v162, v161
	v_lshlrev_b32_e32 v163, 2, v3
	v_add_lshl_u32 v164, v162, v157, 2
	ds_bpermute_b32 v3, v163, v2
	ds_bpermute_b32 v4, v164, v4
	v_mov_b32_e32 v2, v33
	s_and_saveexec_b64 s[42:43], s[0:1]
	s_cbranch_execz .LBB0_2775
	s_waitcnt lgkmcnt(0)
	v_add_f32_e32 v2, v3, v4
	v_cmp_lt_i32_e32 vcc, -1, v2
	s_nop 1
	v_cndmask_b32_e32 v3, -1, v159, vcc
	v_bitop3_b32 v2, v3, s33, v2 bitop3:0x48
	v_bitop3_b32 v2, v2, s54, v156 bitop3:0x36
